# GEMM loop: also moved As10 LDS-DMA pair from LS2(t+1) to next LS1 (4/4 DMA per load segment), LS2 vmcnt 8->6
# baseline (speedup 1.0000x reference)
.LBB0_169:
	s_add_u32 s26, s58, 0x12e00000
	s_addc_u32 s27, s59, 0
	s_add_u32 s28, s58, 0x13200000
	s_addc_u32 s29, s59, 0
	v_bfe_u32 v9, v1, 4, 2
	s_add_u32 s30, s58, 0x13600000
	v_and_b32_e32 v200, 15, v1
	v_lshlrev_b32_e32 v2, 4, v9
	v_lshlrev_b32_e32 v1, 2, v1
	s_addc_u32 s31, s59, 0
	s_and_b32 s38, s16, 3
	s_lshl_b32 s16, s17, 6
	v_lshl_or_b32 v2, v200, 6, v2
	s_lshl_b32 s17, s17, 13
	v_and_b32_e32 v1, 32, v1
	v_bitop3_b32 v13, v2, s17, v1 bitop3:0xde
	s_lshl_b32 s17, s38, 12
	v_bitop3_b32 v14, v2, s17, v1 bitop3:0xde
	v_cndmask_b32_e64 v2, 0, 1, s[34:35]
	s_add_u32 s34, s48, 0x120000
	s_addc_u32 s35, s49, 0
	s_add_i32 s17, s8, 0x18000
	v_lshl_add_u64 v[10:11], s[34:35], 0, v[194:195]
	s_mov_b32 m0, s17
	s_add_i32 s54, s8, 0x1a000
	s_waitcnt vmcnt(2)
	s_barrier
	global_load_lds_dwordx4 v[10:11], off
	v_lshl_add_u64 v[10:11], s[34:35], 0, v[196:197]
	s_add_u32 s34, s0, 0x230000
	s_mov_b32 m0, s54
	s_addc_u32 s35, s1, 0
	s_add_i32 s55, s8, 0x8000
	global_load_lds_dwordx4 v[10:11], off
	v_lshl_add_u64 v[10:11], s[34:35], 0, v[194:195]
	s_mov_b64 s[100:101], s[34:35]
	s_mov_b32 m0, s55
	s_add_i32 s67, s8, 0xa000
	global_load_lds_dwordx4 v[10:11], off
	v_lshl_add_u64 v[10:11], s[34:35], 0, v[196:197]
	s_add_u32 s34, s48, 0x124000
	s_mov_b32 m0, s67
	s_addc_u32 s35, s49, 0
	s_add_i32 s89, s8, 0x1c000
	global_load_lds_dwordx4 v[10:11], off
	v_lshl_add_u64 v[10:11], s[34:35], 0, v[194:195]
	s_mov_b32 m0, s89
	s_add_i32 s90, s8, 0x1e000
	global_load_lds_dwordx4 v[10:11], off
	v_lshl_add_u64 v[10:11], s[34:35], 0, v[196:197]
	s_mov_b32 m0, s90
	s_cmpk_lt_u32 s36, 0x100
	global_load_lds_dwordx4 v[10:11], off
	s_cselect_b64 s[34:35], -1, 0
	s_ashr_i32 s36, s16, 31
	v_or_b32_e32 v202, s16, v200
	v_mov_b32_e32 v203, s36
	v_mov_b32_e32 v205, s36
	v_mov_b32_e32 v207, s36
	v_mov_b32_e32 v209, s36
	s_mov_b64 s[36:37], 0x80
	v_lshlrev_b32_e32 v12, 3, v9
	v_lshl_add_u64 v[210:211], v[202:203], 0, s[36:37]
	s_mov_b64 s[36:37], 0x90
	v_lshlrev_b32_e32 v9, 2, v9
	v_lshl_add_u64 v[212:213], v[202:203], 0, s[36:37]
	s_mov_b64 s[36:37], 0xa0
	v_lshl_or_b32 v241, s38, 4, v9
	v_lshl_add_u64 v[214:215], v[202:203], 0, s[36:37]
	s_mov_b64 s[36:37], 0xb0
	v_lshlrev_b32_e32 v198, 1, v241
	v_lshlrev_b32_e32 v9, 10, v3
	v_lshl_add_u64 v[216:217], v[202:203], 0, s[36:37]
	v_lshl_add_u64 v[10:11], s[58:59], 0, v[198:199]
	s_mov_b64 s[36:37], 0x1b600000
	v_and_b32_e32 v9, 0xfffff800, v9
	v_lshl_add_u64 v[220:221], v[10:11], 0, s[36:37]
	s_add_u32 s36, s20, 0x1800
	v_lshl_add_u32 v4, v4, 7, v9
	v_and_b32_e32 v3, 1, v3
	s_addc_u32 s37, s21, 0
	v_lshl_or_b32 v3, v3, 6, v4
	s_add_u32 s52, s20, 0x3000
	v_lshl_add_u32 v198, v5, 1, v3
	v_lshlrev_b32_e32 v3, 10, v6
	s_addc_u32 s53, s21, 0
	v_and_b32_e32 v3, 0xfffff800, v3
	s_add_u32 s60, s56, 0x14cc6000
	v_lshl_add_u32 v3, v7, 7, v3
	v_and_b32_e32 v4, 1, v6
	s_mov_b64 s[46:47], 0x230000
	s_waitcnt vmcnt(6)
	s_addc_u32 s61, s57, 0
	v_lshl_or_b32 v3, v4, 6, v3
	s_add_u32 s62, s56, 0x8800000
	v_lshl_add_u64 v[222:223], v[198:199], 0, s[46:47]
	v_lshl_add_u32 v198, v8, 1, v3
	v_lshl_or_b32 v1, s38, 5, v12
	v_add_u32_e32 v201, 0xffffbc00, v202
	v_add_u32_e32 v238, 0xffffbc10, v202
	v_add_u32_e32 v239, 0xffffbc20, v202
	v_add_u32_e32 v240, 0xffffbc30, v202
	v_or_b32_e32 v204, 16, v202
	v_or_b32_e32 v206, 32, v202
	v_or_b32_e32 v208, 48, v202
	v_cmp_eq_u32_e64 s[38:39], 0, v200
	v_cmp_lt_u32_e64 s[40:41], 1, v200
	v_cmp_gt_u32_e64 s[42:43], 2, v200
	v_cmp_lt_u32_e64 s[44:45], 13, v200
	v_add_u32_e32 v218, -14, v200
	v_mov_b32_e32 v219, v199
	s_addc_u32 s63, s57, 0
	v_lshl_add_u64 v[224:225], v[198:199], 0, s[46:47]
	v_mov_b64_e32 v[232:233], s[22:23]
	s_movk_i32 s91, 0x3fff
	s_movk_i32 s92, 0xffc2
	s_movk_i32 s93, 0x1800
	s_movk_i32 s94, 0x1ffd
	s_movk_i32 s95, 0xe002
	v_mov_b64_e32 v[226:227], 0x800
	v_mov_b64_e32 v[228:229], 0x7ff
	v_mov_b64_e32 v[230:231], 0x6ff
	v_mov_b32_e32 v242, 0x4000
	v_add_u32_e32 v243, 0, v14
	v_add_u32_e32 v244, 0, v13
	s_mov_b32 s96, s23
	s_barrier
	s_branch .LBB0_172

.LBB0_176:
	s_mov_b32 m0, s55
	v_lshl_add_u64 v[252:253], s[100:101], 0, v[194:195]
	global_load_lds_dwordx4 v[252:253], off
	s_mov_b32 m0, s67
	v_lshl_add_u64 v[252:253], s[100:101], 0, v[196:197]
	global_load_lds_dwordx4 v[252:253], off
	v_add_u32_e32 v130, 0x10000, v243
	v_add_u32_e32 v142, 0x14000, v243
	ds_read_b128 v[146:149], v130
	ds_read_b128 v[150:153], v130 offset:1024
	ds_read_b128 v[154:157], v130 offset:2048
	ds_read_b128 v[158:161], v130 offset:3072
	ds_read_b128 v[130:133], v142
	ds_read_b128 v[134:137], v142 offset:1024
	ds_read_b128 v[138:141], v142 offset:2048
	ds_read_b128 v[142:145], v142 offset:3072
	v_lshl_add_u64 v[246:247], v[234:235], 0, s[80:81]
	s_add_i32 m0, s8, 0xc000
	s_waitcnt lgkmcnt(0)
	ds_read_b128 v[174:177], v244
	ds_read_b128 v[190:193], v244 offset:1024
	ds_read_b128 v[170:173], v244 offset:2048
	ds_read_b128 v[186:189], v244 offset:3072
	ds_read_b128 v[166:169], v244 offset:4096
	ds_read_b128 v[182:185], v244 offset:5120
	ds_read_b128 v[162:165], v244 offset:6144
	ds_read_b128 v[178:181], v244 offset:7168
	global_load_lds_dwordx4 v[246:247], off
	v_lshl_add_u64 v[246:247], v[236:237], 0, s[80:81]
	s_add_i32 m0, s8, 0xe000
	s_nop 0
	global_load_lds_dwordx4 v[246:247], off
	s_waitcnt vmcnt(8)
	s_waitcnt lgkmcnt(0)
	s_barrier
	s_setprio 1
	s_waitcnt lgkmcnt(0)
	v_mfma_f32_16x16x32_bf16 v[118:121], v[146:149], v[174:177], v[118:121]
	v_mfma_f32_16x16x32_bf16 v[126:129], v[154:157], v[174:177], v[126:129]
	v_mfma_f32_16x16x32_bf16 v[102:105], v[146:149], v[170:173], v[102:105]
	v_mfma_f32_16x16x32_bf16 v[110:113], v[154:157], v[170:173], v[110:113]
	v_mfma_f32_16x16x32_bf16 v[86:89], v[146:149], v[166:169], v[86:89]
	v_mfma_f32_16x16x32_bf16 v[94:97], v[154:157], v[166:169], v[94:97]
	v_mfma_f32_16x16x32_bf16 v[70:73], v[146:149], v[162:165], v[70:73]
	v_mfma_f32_16x16x32_bf16 v[78:81], v[154:157], v[162:165], v[78:81]
	v_mfma_f32_16x16x32_bf16 v[118:121], v[150:153], v[190:193], v[118:121]
	v_mfma_f32_16x16x32_bf16 v[126:129], v[158:161], v[190:193], v[126:129]
	v_mfma_f32_16x16x32_bf16 v[102:105], v[150:153], v[186:189], v[102:105]
	v_mfma_f32_16x16x32_bf16 v[110:113], v[158:161], v[186:189], v[110:113]
	v_mfma_f32_16x16x32_bf16 v[86:89], v[150:153], v[182:185], v[86:89]
	v_mfma_f32_16x16x32_bf16 v[94:97], v[158:161], v[182:185], v[94:97]
	v_mfma_f32_16x16x32_bf16 v[70:73], v[150:153], v[178:181], v[70:73]
	v_mfma_f32_16x16x32_bf16 v[78:81], v[158:161], v[178:181], v[78:81]
	s_setprio 0
	s_setprio 1
	v_mfma_f32_16x16x32_bf16 v[122:125], v[130:133], v[174:177], v[122:125]
	v_mfma_f32_16x16x32_bf16 v[114:117], v[138:141], v[174:177], v[114:117]
	v_mfma_f32_16x16x32_bf16 v[106:109], v[130:133], v[170:173], v[106:109]
	v_mfma_f32_16x16x32_bf16 v[98:101], v[138:141], v[170:173], v[98:101]
	v_mfma_f32_16x16x32_bf16 v[90:93], v[130:133], v[166:169], v[90:93]
	v_mfma_f32_16x16x32_bf16 v[82:85], v[138:141], v[166:169], v[82:85]
	v_mfma_f32_16x16x32_bf16 v[74:77], v[130:133], v[162:165], v[74:77]
	v_mfma_f32_16x16x32_bf16 v[66:69], v[138:141], v[162:165], v[66:69]
	v_mfma_f32_16x16x32_bf16 v[122:125], v[134:137], v[190:193], v[122:125]
	v_mfma_f32_16x16x32_bf16 v[114:117], v[142:145], v[190:193], v[114:117]
	v_mfma_f32_16x16x32_bf16 v[106:109], v[134:137], v[186:189], v[106:109]
	v_mfma_f32_16x16x32_bf16 v[98:101], v[142:145], v[186:189], v[98:101]
	v_mfma_f32_16x16x32_bf16 v[90:93], v[134:137], v[182:185], v[90:93]
	v_mfma_f32_16x16x32_bf16 v[82:85], v[142:145], v[182:185], v[82:85]
	v_mfma_f32_16x16x32_bf16 v[74:77], v[134:137], v[178:181], v[74:77]
	v_mfma_f32_16x16x32_bf16 v[66:69], v[142:145], v[178:181], v[66:69]
	s_setprio 0
	s_barrier
	v_cndmask_b32_e64 v246, 0, 1, s[50:51]
	v_cmp_ne_u32_e64 s[48:49], 1, v246
	s_andn2_b64 vcc, exec, s[50:51]
	s_cbranch_vccnz .LBB0_178
	ds_read_b128 v[174:177], v244 offset:16384
	ds_read_b128 v[190:193], v244 offset:17408
	ds_read_b128 v[170:173], v244 offset:18432
	ds_read_b128 v[186:189], v244 offset:19456
	ds_read_b128 v[166:169], v244 offset:20480
	ds_read_b128 v[182:185], v244 offset:21504
	ds_read_b128 v[162:165], v244 offset:22528
	ds_read_b128 v[178:181], v244 offset:23552

.LBB0_182:
	s_add_u32 s86, s82, 0x120000
	s_addc_u32 s87, s83, 0
	s_add_u32 s84, s84, 0x230000
	s_addc_u32 s85, s85, 0
	s_mov_b32 m0, s17
	v_lshl_add_u64 v[246:247], s[86:87], 0, v[194:195]
	s_add_u32 s82, s82, 0x124000
	global_load_lds_dwordx4 v[246:247], off
	v_lshl_add_u64 v[246:247], s[86:87], 0, v[196:197]
	s_mov_b32 m0, s54
	s_addc_u32 s83, s83, 0
	global_load_lds_dwordx4 v[246:247], off
	v_lshl_add_u64 v[246:247], s[82:83], 0, v[194:195]
	s_mov_b32 m0, s89
	s_and_b64 vcc, exec, s[48:49]
	global_load_lds_dwordx4 v[246:247], off
	v_lshl_add_u64 v[246:247], s[82:83], 0, v[196:197]
	s_mov_b32 m0, s90
	s_nop 0
	global_load_lds_dwordx4 v[246:247], off
	s_mov_b64 s[100:101], s[84:85]
	s_waitcnt vmcnt(6)
	s_waitcnt lgkmcnt(0)
	s_barrier
	s_cbranch_vccnz .LBB0_175
	s_setprio 1
	s_waitcnt lgkmcnt(0)
	v_mfma_f32_16x16x32_bf16 v[54:57], v[146:149], v[174:177], v[54:57]
	v_mfma_f32_16x16x32_bf16 v[62:65], v[154:157], v[174:177], v[62:65]
	v_mfma_f32_16x16x32_bf16 v[38:41], v[146:149], v[170:173], v[38:41]
	v_mfma_f32_16x16x32_bf16 v[46:49], v[154:157], v[170:173], v[46:49]
	v_mfma_f32_16x16x32_bf16 v[22:25], v[146:149], v[166:169], v[22:25]
	v_mfma_f32_16x16x32_bf16 v[30:33], v[154:157], v[166:169], v[30:33]
	v_mfma_f32_16x16x32_bf16 v[10:13], v[146:149], v[162:165], v[10:13]
	v_mfma_f32_16x16x32_bf16 v[14:17], v[154:157], v[162:165], v[14:17]
	v_mfma_f32_16x16x32_bf16 v[54:57], v[150:153], v[190:193], v[54:57]
	v_mfma_f32_16x16x32_bf16 v[62:65], v[158:161], v[190:193], v[62:65]
	v_mfma_f32_16x16x32_bf16 v[38:41], v[150:153], v[186:189], v[38:41]
	v_mfma_f32_16x16x32_bf16 v[46:49], v[158:161], v[186:189], v[46:49]
	v_mfma_f32_16x16x32_bf16 v[22:25], v[150:153], v[182:185], v[22:25]
	v_mfma_f32_16x16x32_bf16 v[30:33], v[158:161], v[182:185], v[30:33]
	v_mfma_f32_16x16x32_bf16 v[10:13], v[150:153], v[178:181], v[10:13]
	v_mfma_f32_16x16x32_bf16 v[14:17], v[158:161], v[178:181], v[14:17]
	s_setprio 0
	s_setprio 1
	v_mfma_f32_16x16x32_bf16 v[58:61], v[130:133], v[174:177], v[58:61]
	v_mfma_f32_16x16x32_bf16 v[50:53], v[138:141], v[174:177], v[50:53]
	v_mfma_f32_16x16x32_bf16 v[42:45], v[130:133], v[170:173], v[42:45]
	v_mfma_f32_16x16x32_bf16 v[34:37], v[138:141], v[170:173], v[34:37]
	v_mfma_f32_16x16x32_bf16 v[26:29], v[130:133], v[166:169], v[26:29]
	v_mfma_f32_16x16x32_bf16 v[18:21], v[138:141], v[166:169], v[18:21]
	v_mfma_f32_16x16x32_bf16 v[6:9], v[130:133], v[162:165], v[6:9]
	v_mfma_f32_16x16x32_bf16 v[2:5], v[138:141], v[162:165], v[2:5]
	v_mfma_f32_16x16x32_bf16 v[58:61], v[134:137], v[190:193], v[58:61]
	v_mfma_f32_16x16x32_bf16 v[50:53], v[142:145], v[190:193], v[50:53]
	v_mfma_f32_16x16x32_bf16 v[42:45], v[134:137], v[186:189], v[42:45]
	v_mfma_f32_16x16x32_bf16 v[34:37], v[142:145], v[186:189], v[34:37]
	v_mfma_f32_16x16x32_bf16 v[26:29], v[134:137], v[182:185], v[26:29]
	v_mfma_f32_16x16x32_bf16 v[18:21], v[142:145], v[182:185], v[18:21]
	v_mfma_f32_16x16x32_bf16 v[6:9], v[134:137], v[178:181], v[6:9]
	v_mfma_f32_16x16x32_bf16 v[2:5], v[142:145], v[178:181], v[2:5]
	s_setprio 0
	s_branch .LBB0_175

.LBB0_548:
	s_add_u32 s28, s20, 0x5aa0000
	s_addc_u32 s29, s21, 0
	s_add_u32 s30, s20, 0x1c0000
	s_addc_u32 s31, s21, 0
	s_lshl_b32 s16, s36, 5
	s_and_b32 s16, s16, 0x60
	s_lshl_b32 s1, s35, 13
	s_lshl_b32 s37, s16, 7
	s_add_u32 s38, s44, 0x40000
	s_addc_u32 s39, s45, 0
	s_add_i32 s17, s8, 0x18000
	v_lshl_add_u64 v[10:11], s[38:39], 0, v[194:195]
	s_mov_b32 m0, s17
	s_add_i32 s54, s8, 0x1a000
	s_waitcnt vmcnt(2)
	s_barrier
	global_load_lds_dwordx4 v[10:11], off
	v_lshl_add_u64 v[10:11], s[38:39], 0, v[196:197]
	s_add_u32 s38, s56, 0x220000
	s_mov_b32 m0, s54
	s_addc_u32 s39, s57, 0
	s_add_i32 s55, s8, 0x8000
	global_load_lds_dwordx4 v[10:11], off
	v_lshl_add_u64 v[10:11], s[38:39], 0, v[194:195]
	s_mov_b64 s[100:101], s[38:39]
	s_mov_b32 m0, s55
	s_add_i32 s67, s8, 0xa000
	global_load_lds_dwordx4 v[10:11], off
	v_lshl_add_u64 v[10:11], s[38:39], 0, v[196:197]
	s_add_u32 s38, s44, 0x44000
	s_mov_b32 m0, s67
	s_addc_u32 s39, s45, 0
	s_add_i32 s70, s8, 0x1c000
	global_load_lds_dwordx4 v[10:11], off
	v_lshl_add_u64 v[10:11], s[38:39], 0, v[194:195]
	s_mov_b32 m0, s70
	s_add_i32 s71, s8, 0x1e000
	global_load_lds_dwordx4 v[10:11], off
	v_lshl_add_u64 v[10:11], s[38:39], 0, v[196:197]
	s_mov_b32 m0, s71
	v_and_b32_e32 v9, 15, v2
	global_load_lds_dwordx4 v[10:11], off
	v_bfe_u32 v10, v2, 4, 2
	v_lshlrev_b32_e32 v11, 4, v10
	v_lshlrev_b32_e32 v2, 2, v2
	v_lshl_or_b32 v221, s35, 6, v9
	v_lshl_or_b32 v9, v9, 6, v11
	v_and_b32_e32 v2, 32, v2
	v_bitop3_b32 v12, v9, s1, v2 bitop3:0xde
	v_bitop3_b32 v2, v9, s37, v2 bitop3:0xde
	v_lshlrev_b32_e32 v9, 10, v3
	s_cmpk_lt_u32 s34, 0x100
	v_and_b32_e32 v9, 0xfffff800, v9
	s_cselect_b64 s[34:35], -1, 0
	s_lshl_b32 s1, s36, 6
	v_lshl_add_u32 v4, v4, 7, v9
	v_and_b32_e32 v3, 1, v3
	v_and_or_b32 v198, s1, 64, v11
	v_lshl_or_b32 v3, v3, 6, v4
	v_cmp_eq_u32_e64 s[38:39], 0, v10
	v_lshl_add_u64 v[10:11], s[20:21], 0, v[198:199]
	v_lshl_add_u32 v198, v5, 1, v3
	v_lshlrev_b32_e32 v3, 10, v6
	v_and_b32_e32 v3, 0xfffff800, v3
	v_lshl_add_u32 v3, v7, 7, v3
	v_and_b32_e32 v4, 1, v6
	s_mov_b64 s[40:41], 0x220000
	s_waitcnt vmcnt(6)
	s_mov_b64 s[36:37], 0xa600000
	v_lshl_or_b32 v3, v4, 6, v3
	v_lshl_add_u64 v[200:201], v[10:11], 0, s[36:37]
	s_mov_b64 s[36:37], 0x5b00000
	v_lshl_add_u64 v[204:205], v[198:199], 0, s[40:41]
	v_lshl_add_u32 v198, v8, 1, v3
	v_add_u32_e32 v226, 0, v2
	v_mbcnt_lo_u32_b32 v2, -1, 0
	v_or_b32_e32 v222, 16, v221
	v_or_b32_e32 v223, 32, v221
	v_or_b32_e32 v224, 48, v221
	v_lshl_add_u64 v[202:203], v[10:11], 0, s[36:37]
	v_lshl_add_u64 v[206:207], v[198:199], 0, s[40:41]
	v_mov_b64_e32 v[214:215], s[24:25]
	v_mov_b64_e32 v[208:209], 0x240
	v_mov_b64_e32 v[210:211], 0x23f
	v_mov_b32_e32 v225, 0x4000
	v_add_u32_e32 v227, 0x10000, v226
	v_add_u32_e32 v228, 0x14000, v226
	v_add_u32_e32 v229, 0, v12
	v_mov_b64_e32 v[212:213], 0x1ff
	v_mov_b32_e32 v230, 0x4600
	v_mbcnt_hi_u32_b32 v231, -1, v2
	v_mov_b32_e32 v6, v1
	s_barrier
	s_branch .LBB0_551

.LBB0_559:
	s_mov_b32 m0, s55
	v_lshl_add_u64 v[252:253], s[100:101], 0, v[194:195]
	global_load_lds_dwordx4 v[252:253], off
	s_mov_b32 m0, s67
	v_lshl_add_u64 v[252:253], s[100:101], 0, v[196:197]
	global_load_lds_dwordx4 v[252:253], off
	ds_read_b128 v[146:149], v227
	ds_read_b128 v[150:153], v227 offset:1024
	ds_read_b128 v[154:157], v227 offset:2048
	ds_read_b128 v[158:161], v227 offset:3072
	ds_read_b128 v[130:133], v228
	ds_read_b128 v[134:137], v228 offset:1024
	ds_read_b128 v[138:141], v228 offset:2048
	ds_read_b128 v[142:145], v228 offset:3072
	v_lshl_add_u64 v[234:235], v[216:217], 0, s[58:59]
	s_add_i32 m0, s8, 0xc000
	s_waitcnt lgkmcnt(0)
	ds_read_b128 v[174:177], v229
	ds_read_b128 v[190:193], v229 offset:1024
	ds_read_b128 v[170:173], v229 offset:2048
	ds_read_b128 v[186:189], v229 offset:3072
	ds_read_b128 v[166:169], v229 offset:4096
	ds_read_b128 v[182:185], v229 offset:5120
	ds_read_b128 v[162:165], v229 offset:6144
	ds_read_b128 v[178:181], v229 offset:7168
	global_load_lds_dwordx4 v[234:235], off
	v_lshl_add_u64 v[234:235], v[218:219], 0, s[58:59]
	s_add_i32 m0, s8, 0xe000
	s_nop 0
	global_load_lds_dwordx4 v[234:235], off
	s_waitcnt vmcnt(8)
	s_waitcnt lgkmcnt(0)
	s_barrier
	s_setprio 1
	s_waitcnt lgkmcnt(0)
	v_mfma_f32_16x16x32_bf16 v[126:129], v[146:149], v[174:177], v[126:129]
	v_mfma_f32_16x16x32_bf16 v[122:125], v[154:157], v[174:177], v[122:125]
	v_mfma_f32_16x16x32_bf16 v[110:113], v[146:149], v[170:173], v[110:113]
	v_mfma_f32_16x16x32_bf16 v[106:109], v[154:157], v[170:173], v[106:109]
	v_mfma_f32_16x16x32_bf16 v[94:97], v[146:149], v[166:169], v[94:97]
	v_mfma_f32_16x16x32_bf16 v[90:93], v[154:157], v[166:169], v[90:93]
	v_mfma_f32_16x16x32_bf16 v[78:81], v[146:149], v[162:165], v[78:81]
	v_mfma_f32_16x16x32_bf16 v[74:77], v[154:157], v[162:165], v[74:77]
	v_mfma_f32_16x16x32_bf16 v[126:129], v[150:153], v[190:193], v[126:129]
	v_mfma_f32_16x16x32_bf16 v[122:125], v[158:161], v[190:193], v[122:125]
	v_mfma_f32_16x16x32_bf16 v[110:113], v[150:153], v[186:189], v[110:113]
	v_mfma_f32_16x16x32_bf16 v[106:109], v[158:161], v[186:189], v[106:109]
	v_mfma_f32_16x16x32_bf16 v[94:97], v[150:153], v[182:185], v[94:97]
	v_mfma_f32_16x16x32_bf16 v[90:93], v[158:161], v[182:185], v[90:93]
	v_mfma_f32_16x16x32_bf16 v[78:81], v[150:153], v[178:181], v[78:81]
	v_mfma_f32_16x16x32_bf16 v[74:77], v[158:161], v[178:181], v[74:77]
	s_setprio 0
	s_setprio 1
	v_mfma_f32_16x16x32_bf16 v[118:121], v[130:133], v[174:177], v[118:121]
	v_mfma_f32_16x16x32_bf16 v[114:117], v[138:141], v[174:177], v[114:117]
	v_mfma_f32_16x16x32_bf16 v[102:105], v[130:133], v[170:173], v[102:105]
	v_mfma_f32_16x16x32_bf16 v[98:101], v[138:141], v[170:173], v[98:101]
	v_mfma_f32_16x16x32_bf16 v[86:89], v[130:133], v[166:169], v[86:89]
	v_mfma_f32_16x16x32_bf16 v[82:85], v[138:141], v[166:169], v[82:85]
	v_mfma_f32_16x16x32_bf16 v[70:73], v[130:133], v[162:165], v[70:73]
	v_mfma_f32_16x16x32_bf16 v[66:69], v[138:141], v[162:165], v[66:69]
	v_mfma_f32_16x16x32_bf16 v[118:121], v[134:137], v[190:193], v[118:121]
	v_mfma_f32_16x16x32_bf16 v[114:117], v[142:145], v[190:193], v[114:117]
	v_mfma_f32_16x16x32_bf16 v[102:105], v[134:137], v[186:189], v[102:105]
	v_mfma_f32_16x16x32_bf16 v[98:101], v[142:145], v[186:189], v[98:101]
	v_mfma_f32_16x16x32_bf16 v[86:89], v[134:137], v[182:185], v[86:89]
	v_mfma_f32_16x16x32_bf16 v[82:85], v[142:145], v[182:185], v[82:85]
	v_mfma_f32_16x16x32_bf16 v[70:73], v[134:137], v[178:181], v[70:73]
	v_mfma_f32_16x16x32_bf16 v[66:69], v[142:145], v[178:181], v[66:69]
	s_setprio 0
	s_barrier
	v_cmp_ne_u32_e64 s[42:43], 1, v233
	s_andn2_b64 vcc, exec, s[44:45]
	s_cbranch_vccnz .LBB0_561
	ds_read_b128 v[174:177], v229 offset:16384
	ds_read_b128 v[190:193], v229 offset:17408
	ds_read_b128 v[170:173], v229 offset:18432
	ds_read_b128 v[186:189], v229 offset:19456
	ds_read_b128 v[166:169], v229 offset:20480
	ds_read_b128 v[182:185], v229 offset:21504
	ds_read_b128 v[162:165], v229 offset:22528
	ds_read_b128 v[178:181], v229 offset:23552

.LBB0_565:
	s_add_u32 s68, s60, 0x40000
	s_addc_u32 s69, s61, 0
	s_add_u32 s62, s62, 0x220000
	s_addc_u32 s63, s63, 0
	s_mov_b32 m0, s17
	v_lshl_add_u64 v[234:235], s[68:69], 0, v[194:195]
	s_add_u32 s60, s60, 0x44000
	global_load_lds_dwordx4 v[234:235], off
	v_lshl_add_u64 v[234:235], s[68:69], 0, v[196:197]
	s_mov_b32 m0, s54
	s_addc_u32 s61, s61, 0
	global_load_lds_dwordx4 v[234:235], off
	v_lshl_add_u64 v[234:235], s[60:61], 0, v[194:195]
	s_mov_b32 m0, s70
	s_and_b64 vcc, exec, s[42:43]
	global_load_lds_dwordx4 v[234:235], off
	v_lshl_add_u64 v[234:235], s[60:61], 0, v[196:197]
	s_mov_b32 m0, s71
	s_nop 0
	global_load_lds_dwordx4 v[234:235], off
	s_mov_b64 s[100:101], s[62:63]
	s_waitcnt vmcnt(6)
	s_waitcnt lgkmcnt(0)
	s_barrier
	s_cbranch_vccnz .LBB0_558
	s_setprio 1
	s_waitcnt lgkmcnt(0)
	v_mfma_f32_16x16x32_bf16 v[62:65], v[146:149], v[174:177], v[62:65]
	v_mfma_f32_16x16x32_bf16 v[58:61], v[154:157], v[174:177], v[58:61]
	v_mfma_f32_16x16x32_bf16 v[46:49], v[146:149], v[170:173], v[46:49]
	v_mfma_f32_16x16x32_bf16 v[42:45], v[154:157], v[170:173], v[42:45]
	v_mfma_f32_16x16x32_bf16 v[30:33], v[146:149], v[166:169], v[30:33]
	v_mfma_f32_16x16x32_bf16 v[26:29], v[154:157], v[166:169], v[26:29]
	v_mfma_f32_16x16x32_bf16 v[14:17], v[146:149], v[162:165], v[14:17]
	v_mfma_f32_16x16x32_bf16 v[10:13], v[154:157], v[162:165], v[10:13]
	v_mfma_f32_16x16x32_bf16 v[62:65], v[150:153], v[190:193], v[62:65]
	v_mfma_f32_16x16x32_bf16 v[58:61], v[158:161], v[190:193], v[58:61]
	v_mfma_f32_16x16x32_bf16 v[46:49], v[150:153], v[186:189], v[46:49]
	v_mfma_f32_16x16x32_bf16 v[42:45], v[158:161], v[186:189], v[42:45]
	v_mfma_f32_16x16x32_bf16 v[30:33], v[150:153], v[182:185], v[30:33]
	v_mfma_f32_16x16x32_bf16 v[26:29], v[158:161], v[182:185], v[26:29]
	v_mfma_f32_16x16x32_bf16 v[14:17], v[150:153], v[178:181], v[14:17]
	v_mfma_f32_16x16x32_bf16 v[10:13], v[158:161], v[178:181], v[10:13]
	s_setprio 0
	s_setprio 1
	v_mfma_f32_16x16x32_bf16 v[54:57], v[130:133], v[174:177], v[54:57]
	v_mfma_f32_16x16x32_bf16 v[50:53], v[138:141], v[174:177], v[50:53]
	v_mfma_f32_16x16x32_bf16 v[38:41], v[130:133], v[170:173], v[38:41]
	v_mfma_f32_16x16x32_bf16 v[34:37], v[138:141], v[170:173], v[34:37]
	v_mfma_f32_16x16x32_bf16 v[22:25], v[130:133], v[166:169], v[22:25]
	v_mfma_f32_16x16x32_bf16 v[18:21], v[138:141], v[166:169], v[18:21]
	v_mfma_f32_16x16x32_bf16 v[6:9], v[130:133], v[162:165], v[6:9]
	v_mfma_f32_16x16x32_bf16 v[2:5], v[138:141], v[162:165], v[2:5]
	v_mfma_f32_16x16x32_bf16 v[54:57], v[134:137], v[190:193], v[54:57]
	v_mfma_f32_16x16x32_bf16 v[50:53], v[142:145], v[190:193], v[50:53]
	v_mfma_f32_16x16x32_bf16 v[38:41], v[134:137], v[186:189], v[38:41]
	v_mfma_f32_16x16x32_bf16 v[34:37], v[142:145], v[186:189], v[34:37]
	v_mfma_f32_16x16x32_bf16 v[22:25], v[134:137], v[182:185], v[22:25]
	v_mfma_f32_16x16x32_bf16 v[18:21], v[142:145], v[182:185], v[18:21]
	v_mfma_f32_16x16x32_bf16 v[6:9], v[134:137], v[178:181], v[6:9]
	v_mfma_f32_16x16x32_bf16 v[2:5], v[142:145], v[178:181], v[2:5]
	s_setprio 0
	s_branch .LBB0_558

.LBB0_755:
	s_lshl_b32 s14, s14, 5
	s_and_b32 s28, s14, 0x60
	s_lshl_b32 s23, s17, 13
	s_lshl_b32 s29, s28, 7
	s_add_u32 s14, s0, 0xe0000
	s_addc_u32 s15, s1, 0
	s_add_i32 m0, s9, 0x18000
	v_lshl_add_u64 v[10:11], s[14:15], 0, v[194:195]
	s_waitcnt vmcnt(2)
	s_barrier
	global_load_lds_dwordx4 v[10:11], off
	s_add_i32 m0, s9, 0x1a000
	s_add_u32 s26, s42, 0x220000
	v_lshl_add_u64 v[10:11], s[14:15], 0, v[196:197]
	s_addc_u32 s27, s43, 0
	s_add_i32 s14, s9, 0x8000
	global_load_lds_dwordx4 v[10:11], off
	v_lshl_add_u64 v[10:11], s[26:27], 0, v[194:195]
	s_mov_b64 s[100:101], s[26:27]
	s_mov_b32 m0, s14
	s_add_i32 s15, s9, 0xa000
	global_load_lds_dwordx4 v[10:11], off
	v_lshl_add_u64 v[10:11], s[26:27], 0, v[196:197]
	s_add_u32 s26, s0, 0xe4000
	s_mov_b32 m0, s15
	s_addc_u32 s27, s1, 0
	global_load_lds_dwordx4 v[10:11], off
	s_add_i32 m0, s9, 0x1c000
	v_lshl_add_u64 v[10:11], s[26:27], 0, v[194:195]
	global_load_lds_dwordx4 v[10:11], off
	v_lshl_add_u64 v[10:11], s[26:27], 0, v[196:197]
	s_add_i32 m0, s9, 0x1e000
	v_and_b32_e32 v9, 15, v2
	global_load_lds_dwordx4 v[10:11], off
	v_bfe_u32 v10, v2, 4, 2
	v_lshlrev_b32_e32 v11, 4, v10
	v_lshlrev_b32_e32 v2, 2, v2
	v_lshl_or_b32 v227, s17, 6, v9
	v_lshl_or_b32 v9, v9, 6, v11
	v_and_b32_e32 v2, 32, v2
	v_bitop3_b32 v11, v9, s23, v2 bitop3:0xde
	v_bitop3_b32 v228, v9, s29, v2 bitop3:0xde
	v_lshlrev_b32_e32 v2, 10, v6
	v_and_b32_e32 v2, 0xfffff800, v2
	v_lshl_add_u32 v2, v7, 7, v2
	v_and_b32_e32 v6, 1, v6
	v_lshl_or_b32 v2, v6, 6, v2
	v_lshl_add_u32 v200, v8, 1, v2
	v_lshlrev_b32_e32 v2, 10, v3
	v_and_b32_e32 v2, 0xfffff800, v2
	v_lshl_add_u32 v2, v4, 7, v2
	v_and_b32_e32 v3, 1, v3
	s_waitcnt vmcnt(6)
	s_cmpk_lt_u32 s16, 0x100
	v_lshl_or_b32 v2, v3, 6, v2
	s_cselect_b64 s[26:27], -1, 0
	v_lshl_add_u32 v202, v5, 1, v2
	s_add_i32 s16, 0, 0x10000
	s_add_i32 s17, 0, 0x14000
	v_mbcnt_lo_u32_b32 v2, -1, 0
	v_lshl_or_b32 v229, v10, 3, s28
	v_or_b32_e32 v230, 16, v227
	v_or_b32_e32 v231, 32, v227
	v_or_b32_e32 v232, 48, v227
	v_add_u32_e32 v233, 0x80, v227
	v_add_u32_e32 v234, 0x90, v227
	v_add_u32_e32 v235, 0xa0, v227
	v_add_u32_e32 v236, 0xb0, v227
	v_cmp_eq_u32_e64 s[38:39], 0, v10
	v_mov_b32_e32 v201, v199
	v_mov_b32_e32 v203, v199
	v_mov_b64_e32 v[204:205], 0x700
	v_mov_b64_e32 v[206:207], 0x6ff
	v_add_u32_e32 v237, s16, v228
	v_add_u32_e32 v238, s17, v228
	v_add_u32_e32 v239, 0, v11
	v_mov_b32_e32 v240, 0x358637bd
	s_mov_b32 s23, 0xf800000
	v_mov_b32_e32 v241, 0x260
	s_movk_i32 s54, 0x600
	v_mbcnt_hi_u32_b32 v242, -1, v2
	s_barrier
	s_branch .LBB0_758

.LBB0_761:
	s_mov_b32 m0, s14
	v_lshl_add_u64 v[252:253], s[100:101], 0, v[194:195]
	global_load_lds_dwordx4 v[252:253], off
	s_mov_b32 m0, s15
	v_lshl_add_u64 v[252:253], s[100:101], 0, v[196:197]
	global_load_lds_dwordx4 v[252:253], off
	ds_read_b128 v[130:133], v237
	ds_read_b128 v[134:137], v237 offset:1024
	ds_read_b128 v[138:141], v237 offset:2048
	ds_read_b128 v[142:145], v237 offset:3072
	ds_read_b128 v[146:149], v238
	ds_read_b128 v[150:153], v238 offset:1024
	ds_read_b128 v[154:157], v238 offset:2048
	ds_read_b128 v[158:161], v238 offset:3072
	s_add_u32 s48, s0, 0x21c000
	s_addc_u32 s49, s1, 0
	s_cmp_eq_u32 s67, 28
	s_cselect_b32 s42, s55, s62
	s_cselect_b32 s43, s29, s63
	s_cselect_b32 s52, s45, s48
	s_cselect_b32 s53, s31, s49
	s_add_u32 s50, s42, 0xe0000
	s_addc_u32 s51, s43, 0
	s_add_u32 s48, s52, 0x220000
	s_addc_u32 s49, s53, 0
	v_lshl_add_u64 v[208:209], s[0:1], 0, v[202:203]
	s_add_i32 m0, s9, 0xc000
	ds_read_b128 v[162:165], v239
	ds_read_b128 v[166:169], v239 offset:1024
	ds_read_b128 v[170:173], v239 offset:2048
	ds_read_b128 v[174:177], v239 offset:3072
	ds_read_b128 v[178:181], v239 offset:4096
	ds_read_b128 v[182:185], v239 offset:5120
	ds_read_b128 v[186:189], v239 offset:6144
	ds_read_b128 v[190:193], v239 offset:7168
	global_load_lds_dwordx4 v[208:209], off
	v_lshl_add_u64 v[208:209], s[0:1], 0, v[200:201]
	s_add_i32 m0, s9, 0xe000
	s_nop 0
	global_load_lds_dwordx4 v[208:209], off
	s_waitcnt vmcnt(8)
	s_waitcnt lgkmcnt(0)
	s_barrier
	s_setprio 1
	s_waitcnt lgkmcnt(0)
	v_mfma_f32_16x16x32_bf16 v[126:129], v[130:133], v[162:165], v[126:129]
	v_mfma_f32_16x16x32_bf16 v[122:125], v[138:141], v[162:165], v[122:125]
	v_mfma_f32_16x16x32_bf16 v[118:121], v[130:133], v[170:173], v[118:121]
	v_mfma_f32_16x16x32_bf16 v[114:117], v[138:141], v[170:173], v[114:117]
	v_mfma_f32_16x16x32_bf16 v[110:113], v[130:133], v[178:181], v[110:113]
	v_mfma_f32_16x16x32_bf16 v[106:109], v[138:141], v[178:181], v[106:109]
	v_mfma_f32_16x16x32_bf16 v[102:105], v[130:133], v[186:189], v[102:105]
	v_mfma_f32_16x16x32_bf16 v[98:101], v[138:141], v[186:189], v[98:101]
	v_mfma_f32_16x16x32_bf16 v[126:129], v[134:137], v[166:169], v[126:129]
	v_mfma_f32_16x16x32_bf16 v[122:125], v[142:145], v[166:169], v[122:125]
	v_mfma_f32_16x16x32_bf16 v[118:121], v[134:137], v[174:177], v[118:121]
	v_mfma_f32_16x16x32_bf16 v[114:117], v[142:145], v[174:177], v[114:117]
	v_mfma_f32_16x16x32_bf16 v[110:113], v[134:137], v[182:185], v[110:113]
	v_mfma_f32_16x16x32_bf16 v[106:109], v[142:145], v[182:185], v[106:109]
	v_mfma_f32_16x16x32_bf16 v[102:105], v[134:137], v[190:193], v[102:105]
	v_mfma_f32_16x16x32_bf16 v[98:101], v[142:145], v[190:193], v[98:101]
	s_setprio 0
	s_setprio 1
	v_mfma_f32_16x16x32_bf16 v[62:65], v[146:149], v[162:165], v[62:65]
	s_add_u32 s60, s52, 0x4000
	s_addc_u32 s61, s53, 0
	v_mfma_f32_16x16x32_bf16 v[58:61], v[154:157], v[162:165], v[58:61]
	v_mfma_f32_16x16x32_bf16 v[54:57], v[146:149], v[170:173], v[54:57]
	v_mfma_f32_16x16x32_bf16 v[50:53], v[154:157], v[170:173], v[50:53]
	v_mfma_f32_16x16x32_bf16 v[46:49], v[146:149], v[178:181], v[46:49]
	v_mfma_f32_16x16x32_bf16 v[42:45], v[154:157], v[178:181], v[42:45]
	v_mfma_f32_16x16x32_bf16 v[38:41], v[146:149], v[186:189], v[38:41]
	v_mfma_f32_16x16x32_bf16 v[34:37], v[154:157], v[186:189], v[34:37]
	v_mfma_f32_16x16x32_bf16 v[62:65], v[150:153], v[166:169], v[62:65]
	v_mfma_f32_16x16x32_bf16 v[58:61], v[158:161], v[166:169], v[58:61]
	v_mfma_f32_16x16x32_bf16 v[54:57], v[150:153], v[174:177], v[54:57]
	v_mfma_f32_16x16x32_bf16 v[50:53], v[158:161], v[174:177], v[50:53]
	v_mfma_f32_16x16x32_bf16 v[46:49], v[150:153], v[182:185], v[46:49]
	v_mfma_f32_16x16x32_bf16 v[42:45], v[158:161], v[182:185], v[42:45]
	v_mfma_f32_16x16x32_bf16 v[38:41], v[150:153], v[190:193], v[38:41]
	v_mfma_f32_16x16x32_bf16 v[34:37], v[158:161], v[190:193], v[34:37]
	s_setprio 0
	s_barrier
	s_add_i32 s68, s16, s8
	v_lshl_add_u64 v[208:209], s[42:43], 0, v[194:195]
	s_mov_b32 m0, s68
	ds_read_b128 v[162:165], v239 offset:16384
	ds_read_b128 v[166:169], v239 offset:17408
	ds_read_b128 v[170:173], v239 offset:18432
	ds_read_b128 v[174:177], v239 offset:19456
	ds_read_b128 v[178:181], v239 offset:20480
	ds_read_b128 v[182:185], v239 offset:21504
	ds_read_b128 v[186:189], v239 offset:22528
	ds_read_b128 v[190:193], v239 offset:23552
	global_load_lds_dwordx4 v[208:209], off
	s_add_i32 m0, s68, 0x2000
	s_add_u32 s68, s42, 0x4000
	v_lshl_add_u64 v[208:209], s[42:43], 0, v[196:197]
	s_addc_u32 s69, s43, 0
	s_add_i32 s70, s17, s8
	global_load_lds_dwordx4 v[208:209], off
	v_lshl_add_u64 v[208:209], s[68:69], 0, v[194:195]
	s_mov_b32 m0, s70
	s_nop 0
	global_load_lds_dwordx4 v[208:209], off
	v_lshl_add_u64 v[208:209], s[68:69], 0, v[196:197]
	s_add_i32 m0, s70, 0x2000
	s_nop 0
	global_load_lds_dwordx4 v[208:209], off
	s_mov_b64 s[98:99], s[52:53]
	s_waitcnt vmcnt(6)
	s_waitcnt lgkmcnt(0)
	s_barrier
	s_setprio 1
	s_waitcnt lgkmcnt(0)
	v_mfma_f32_16x16x32_bf16 v[94:97], v[130:133], v[162:165], v[94:97]
	v_mfma_f32_16x16x32_bf16 v[90:93], v[138:141], v[162:165], v[90:93]
	v_mfma_f32_16x16x32_bf16 v[86:89], v[130:133], v[170:173], v[86:89]
	v_mfma_f32_16x16x32_bf16 v[82:85], v[138:141], v[170:173], v[82:85]
	v_mfma_f32_16x16x32_bf16 v[78:81], v[130:133], v[178:181], v[78:81]
	v_mfma_f32_16x16x32_bf16 v[74:77], v[138:141], v[178:181], v[74:77]
	v_mfma_f32_16x16x32_bf16 v[70:73], v[130:133], v[186:189], v[70:73]
	v_mfma_f32_16x16x32_bf16 v[66:69], v[138:141], v[186:189], v[66:69]
	v_mfma_f32_16x16x32_bf16 v[94:97], v[134:137], v[166:169], v[94:97]
	v_mfma_f32_16x16x32_bf16 v[90:93], v[142:145], v[166:169], v[90:93]
	v_mfma_f32_16x16x32_bf16 v[86:89], v[134:137], v[174:177], v[86:89]
	v_mfma_f32_16x16x32_bf16 v[82:85], v[142:145], v[174:177], v[82:85]
	v_mfma_f32_16x16x32_bf16 v[78:81], v[134:137], v[182:185], v[78:81]
	v_mfma_f32_16x16x32_bf16 v[74:77], v[142:145], v[182:185], v[74:77]
	v_mfma_f32_16x16x32_bf16 v[70:73], v[134:137], v[190:193], v[70:73]
	v_mfma_f32_16x16x32_bf16 v[66:69], v[142:145], v[190:193], v[66:69]
	s_setprio 0
	s_setprio 1
	v_mfma_f32_16x16x32_bf16 v[30:33], v[146:149], v[162:165], v[30:33]
	v_mfma_f32_16x16x32_bf16 v[26:29], v[154:157], v[162:165], v[26:29]
	v_mfma_f32_16x16x32_bf16 v[22:25], v[146:149], v[170:173], v[22:25]
	v_mfma_f32_16x16x32_bf16 v[18:21], v[154:157], v[170:173], v[18:21]
	v_mfma_f32_16x16x32_bf16 v[14:17], v[146:149], v[178:181], v[14:17]
	v_mfma_f32_16x16x32_bf16 v[10:13], v[154:157], v[178:181], v[10:13]
	v_mfma_f32_16x16x32_bf16 v[6:9], v[146:149], v[186:189], v[6:9]
	v_mfma_f32_16x16x32_bf16 v[2:5], v[154:157], v[186:189], v[2:5]
	v_mfma_f32_16x16x32_bf16 v[30:33], v[150:153], v[166:169], v[30:33]
	v_mfma_f32_16x16x32_bf16 v[26:29], v[158:161], v[166:169], v[26:29]
	v_mfma_f32_16x16x32_bf16 v[22:25], v[150:153], v[174:177], v[22:25]
	v_mfma_f32_16x16x32_bf16 v[18:21], v[158:161], v[174:177], v[18:21]
	v_mfma_f32_16x16x32_bf16 v[14:17], v[150:153], v[182:185], v[14:17]
	v_mfma_f32_16x16x32_bf16 v[10:13], v[158:161], v[182:185], v[10:13]
	v_mfma_f32_16x16x32_bf16 v[6:9], v[150:153], v[190:193], v[6:9]
	v_mfma_f32_16x16x32_bf16 v[2:5], v[158:161], v[190:193], v[2:5]
	s_setprio 0
	s_barrier
	s_mov_b32 m0, s9
	v_lshl_add_u64 v[252:253], s[98:99], 0, v[194:195]
	global_load_lds_dwordx4 v[252:253], off
	s_mov_b32 m0, s10
	v_lshl_add_u64 v[252:253], s[98:99], 0, v[196:197]
	global_load_lds_dwordx4 v[252:253], off
	s_add_i32 s52, 0, 0x18000
	s_add_i32 s53, 0, 0x1c000
	v_add_u32_e32 v142, s52, v228
	v_add_u32_e32 v158, s53, v228
	ds_read_b128 v[130:133], v142
	ds_read_b128 v[134:137], v142 offset:1024
	ds_read_b128 v[138:141], v142 offset:2048
	ds_read_b128 v[142:145], v142 offset:3072
	ds_read_b128 v[146:149], v158
	ds_read_b128 v[150:153], v158 offset:1024
	ds_read_b128 v[154:157], v158 offset:2048
	ds_read_b128 v[158:161], v158 offset:3072
	s_mov_b32 m0, s11
	v_lshl_add_u64 v[208:209], s[60:61], 0, v[194:195]
	ds_read_b128 v[162:165], v239 offset:32768
	ds_read_b128 v[166:169], v239 offset:33792
	ds_read_b128 v[170:173], v239 offset:34816
	ds_read_b128 v[174:177], v239 offset:35840
	ds_read_b128 v[178:181], v239 offset:36864
	ds_read_b128 v[182:185], v239 offset:37888
	ds_read_b128 v[186:189], v239 offset:38912
	ds_read_b128 v[190:193], v239 offset:39936
	global_load_lds_dwordx4 v[208:209], off
	v_lshl_add_u64 v[208:209], s[60:61], 0, v[196:197]
	s_mov_b32 m0, s12
	s_nop 0
	global_load_lds_dwordx4 v[208:209], off
	s_waitcnt vmcnt(8)
	s_waitcnt lgkmcnt(0)
	s_barrier
	s_setprio 1
	s_waitcnt lgkmcnt(0)
	v_mfma_f32_16x16x32_bf16 v[126:129], v[130:133], v[162:165], v[126:129]
	v_mfma_f32_16x16x32_bf16 v[122:125], v[138:141], v[162:165], v[122:125]
	v_mfma_f32_16x16x32_bf16 v[118:121], v[130:133], v[170:173], v[118:121]
	v_mfma_f32_16x16x32_bf16 v[114:117], v[138:141], v[170:173], v[114:117]
	v_mfma_f32_16x16x32_bf16 v[110:113], v[130:133], v[178:181], v[110:113]
	v_mfma_f32_16x16x32_bf16 v[106:109], v[138:141], v[178:181], v[106:109]
	v_mfma_f32_16x16x32_bf16 v[102:105], v[130:133], v[186:189], v[102:105]
	v_mfma_f32_16x16x32_bf16 v[98:101], v[138:141], v[186:189], v[98:101]
	v_mfma_f32_16x16x32_bf16 v[126:129], v[134:137], v[166:169], v[126:129]
	v_mfma_f32_16x16x32_bf16 v[122:125], v[142:145], v[166:169], v[122:125]
	v_mfma_f32_16x16x32_bf16 v[118:121], v[134:137], v[174:177], v[118:121]
	v_mfma_f32_16x16x32_bf16 v[114:117], v[142:145], v[174:177], v[114:117]
	v_mfma_f32_16x16x32_bf16 v[110:113], v[134:137], v[182:185], v[110:113]
	v_mfma_f32_16x16x32_bf16 v[106:109], v[142:145], v[182:185], v[106:109]
	v_mfma_f32_16x16x32_bf16 v[102:105], v[134:137], v[190:193], v[102:105]
	v_mfma_f32_16x16x32_bf16 v[98:101], v[142:145], v[190:193], v[98:101]
	s_setprio 0
	s_setprio 1
	v_mfma_f32_16x16x32_bf16 v[62:65], v[146:149], v[162:165], v[62:65]
	v_mfma_f32_16x16x32_bf16 v[58:61], v[154:157], v[162:165], v[58:61]
	v_mfma_f32_16x16x32_bf16 v[54:57], v[146:149], v[170:173], v[54:57]
	v_mfma_f32_16x16x32_bf16 v[50:53], v[154:157], v[170:173], v[50:53]
	v_mfma_f32_16x16x32_bf16 v[46:49], v[146:149], v[178:181], v[46:49]
	v_mfma_f32_16x16x32_bf16 v[42:45], v[154:157], v[178:181], v[42:45]
	v_mfma_f32_16x16x32_bf16 v[38:41], v[146:149], v[186:189], v[38:41]
	v_mfma_f32_16x16x32_bf16 v[34:37], v[154:157], v[186:189], v[34:37]
	v_mfma_f32_16x16x32_bf16 v[62:65], v[150:153], v[166:169], v[62:65]
	v_mfma_f32_16x16x32_bf16 v[58:61], v[158:161], v[166:169], v[58:61]
	v_mfma_f32_16x16x32_bf16 v[54:57], v[150:153], v[174:177], v[54:57]
	v_mfma_f32_16x16x32_bf16 v[50:53], v[158:161], v[174:177], v[50:53]
	v_mfma_f32_16x16x32_bf16 v[46:49], v[150:153], v[182:185], v[46:49]
	v_mfma_f32_16x16x32_bf16 v[42:45], v[158:161], v[182:185], v[42:45]
	v_mfma_f32_16x16x32_bf16 v[38:41], v[150:153], v[190:193], v[38:41]
	v_mfma_f32_16x16x32_bf16 v[34:37], v[158:161], v[190:193], v[34:37]
	s_setprio 0
	s_barrier
	s_add_i32 s52, s52, s8
	v_lshl_add_u64 v[208:209], s[50:51], 0, v[194:195]
	s_mov_b32 m0, s52
	ds_read_b128 v[162:165], v239 offset:49152
	ds_read_b128 v[166:169], v239 offset:50176
	ds_read_b128 v[170:173], v239 offset:51200
	ds_read_b128 v[174:177], v239 offset:52224
	ds_read_b128 v[178:181], v239 offset:53248
	ds_read_b128 v[182:185], v239 offset:54272
	ds_read_b128 v[186:189], v239 offset:55296
	ds_read_b128 v[190:193], v239 offset:56320
	global_load_lds_dwordx4 v[208:209], off
	s_add_i32 m0, s52, 0x2000
	s_add_u32 s42, s42, 0xe4000
	v_lshl_add_u64 v[208:209], s[50:51], 0, v[196:197]
	s_addc_u32 s43, s43, 0
	s_add_i32 s50, s53, s8
	global_load_lds_dwordx4 v[208:209], off
	v_lshl_add_u64 v[208:209], s[42:43], 0, v[194:195]
	s_mov_b32 m0, s50
	s_nop 0
	global_load_lds_dwordx4 v[208:209], off
	v_lshl_add_u64 v[208:209], s[42:43], 0, v[196:197]
	s_add_i32 m0, s50, 0x2000
	s_nop 0
	global_load_lds_dwordx4 v[208:209], off
	s_mov_b64 s[100:101], s[48:49]
	s_waitcnt vmcnt(6)
	s_waitcnt lgkmcnt(0)
	s_barrier
	s_setprio 1
	s_waitcnt lgkmcnt(0)
	v_mfma_f32_16x16x32_bf16 v[94:97], v[130:133], v[162:165], v[94:97]
	v_mfma_f32_16x16x32_bf16 v[90:93], v[138:141], v[162:165], v[90:93]
	v_mfma_f32_16x16x32_bf16 v[86:89], v[130:133], v[170:173], v[86:89]
	v_mfma_f32_16x16x32_bf16 v[82:85], v[138:141], v[170:173], v[82:85]
	v_mfma_f32_16x16x32_bf16 v[78:81], v[130:133], v[178:181], v[78:81]
	v_mfma_f32_16x16x32_bf16 v[74:77], v[138:141], v[178:181], v[74:77]
	v_mfma_f32_16x16x32_bf16 v[70:73], v[130:133], v[186:189], v[70:73]
	v_mfma_f32_16x16x32_bf16 v[66:69], v[138:141], v[186:189], v[66:69]
	v_mfma_f32_16x16x32_bf16 v[94:97], v[134:137], v[166:169], v[94:97]
	v_mfma_f32_16x16x32_bf16 v[90:93], v[142:145], v[166:169], v[90:93]
	v_mfma_f32_16x16x32_bf16 v[86:89], v[134:137], v[174:177], v[86:89]
	v_mfma_f32_16x16x32_bf16 v[82:85], v[142:145], v[174:177], v[82:85]
	v_mfma_f32_16x16x32_bf16 v[78:81], v[134:137], v[182:185], v[78:81]
	v_mfma_f32_16x16x32_bf16 v[74:77], v[142:145], v[182:185], v[74:77]
	v_mfma_f32_16x16x32_bf16 v[70:73], v[134:137], v[190:193], v[70:73]
	v_mfma_f32_16x16x32_bf16 v[66:69], v[142:145], v[190:193], v[66:69]
	s_setprio 0
	s_setprio 1
	v_mfma_f32_16x16x32_bf16 v[30:33], v[146:149], v[162:165], v[30:33]
	v_mfma_f32_16x16x32_bf16 v[26:29], v[154:157], v[162:165], v[26:29]
	v_mfma_f32_16x16x32_bf16 v[22:25], v[146:149], v[170:173], v[22:25]
	v_mfma_f32_16x16x32_bf16 v[18:21], v[154:157], v[170:173], v[18:21]
	v_mfma_f32_16x16x32_bf16 v[14:17], v[146:149], v[178:181], v[14:17]
	v_mfma_f32_16x16x32_bf16 v[10:13], v[154:157], v[178:181], v[10:13]
	v_mfma_f32_16x16x32_bf16 v[6:9], v[146:149], v[186:189], v[6:9]
	v_mfma_f32_16x16x32_bf16 v[2:5], v[154:157], v[186:189], v[2:5]
	v_mfma_f32_16x16x32_bf16 v[30:33], v[150:153], v[166:169], v[30:33]
	v_mfma_f32_16x16x32_bf16 v[26:29], v[158:161], v[166:169], v[26:29]
	v_mfma_f32_16x16x32_bf16 v[22:25], v[150:153], v[174:177], v[22:25]
	v_mfma_f32_16x16x32_bf16 v[18:21], v[158:161], v[174:177], v[18:21]
	v_mfma_f32_16x16x32_bf16 v[14:17], v[150:153], v[182:185], v[14:17]
	v_mfma_f32_16x16x32_bf16 v[10:13], v[158:161], v[182:185], v[10:13]
	v_mfma_f32_16x16x32_bf16 v[6:9], v[150:153], v[190:193], v[6:9]
	v_mfma_f32_16x16x32_bf16 v[2:5], v[158:161], v[190:193], v[2:5]
	s_setprio 0
	s_barrier
	s_add_i32 s67, s67, 2
	s_add_u32 s62, s62, 0x1c0000
	s_addc_u32 s63, s63, 0
	s_add_u32 s0, s0, 0x440000
	s_addc_u32 s1, s1, 0
	s_cmp_gt_u32 s67, 29
	s_cbranch_scc0 .LBB0_761
	s_and_b64 vcc, exec, s[26:27]
	s_cbranch_vccz .LBB0_764
	s_barrier

.LBB0_896:
	s_lshl_b32 s16, s16, 5
	s_and_b32 s39, s16, 0x60
	s_lshl_b32 s38, s35, 13
	s_lshl_b32 s40, s39, 7
	s_add_u32 s36, s42, 0xe0000
	s_addc_u32 s37, s43, 0
	s_add_i32 s16, s8, 0x18000
	v_lshl_add_u64 v[10:11], s[36:37], 0, v[194:195]
	s_mov_b32 m0, s16
	s_add_i32 s17, s8, 0x1a000
	s_waitcnt vmcnt(2)
	s_barrier
	global_load_lds_dwordx4 v[10:11], off
	v_lshl_add_u64 v[10:11], s[36:37], 0, v[196:197]
	s_add_u32 s36, s0, 0x220000
	s_mov_b32 m0, s17
	s_addc_u32 s37, s1, 0
	s_add_i32 s23, s8, 0x8000
	global_load_lds_dwordx4 v[10:11], off
	v_lshl_add_u64 v[10:11], s[36:37], 0, v[194:195]
	s_mov_b64 s[100:101], s[36:37]
	s_mov_b32 m0, s23
	s_add_i32 s31, s8, 0xa000
	global_load_lds_dwordx4 v[10:11], off
	v_lshl_add_u64 v[10:11], s[36:37], 0, v[196:197]
	s_add_u32 s36, s42, 0xe4000
	s_mov_b32 m0, s31
	s_addc_u32 s37, s43, 0
	s_add_i32 s54, s8, 0x1c000
	global_load_lds_dwordx4 v[10:11], off
	v_lshl_add_u64 v[10:11], s[36:37], 0, v[194:195]
	s_mov_b32 m0, s54
	s_add_i32 s55, s8, 0x1e000
	global_load_lds_dwordx4 v[10:11], off
	v_lshl_add_u64 v[10:11], s[36:37], 0, v[196:197]
	s_mov_b32 m0, s55
	v_and_b32_e32 v6, 15, v2
	global_load_lds_dwordx4 v[10:11], off
	v_bfe_u32 v10, v2, 4, 2
	v_lshlrev_b32_e32 v11, 4, v10
	v_lshlrev_b32_e32 v2, 2, v2
	v_lshl_or_b32 v214, s35, 6, v6
	v_lshl_or_b32 v6, v6, 6, v11
	v_and_b32_e32 v2, 32, v2
	v_bitop3_b32 v11, v6, s38, v2 bitop3:0xde
	v_lshl_or_b32 v215, v10, 3, s39
	v_cmp_eq_u32_e64 s[38:39], 0, v10
	v_lshlrev_b32_e32 v10, 10, v3
	v_and_b32_e32 v10, 0xfffff800, v10
	v_lshl_add_u32 v4, v4, 7, v10
	v_and_b32_e32 v3, 1, v3
	v_lshl_or_b32 v3, v3, 6, v4
	v_lshl_add_u32 v198, v5, 1, v3
	v_lshlrev_b32_e32 v3, 10, v7
	v_and_b32_e32 v3, 0xfffff800, v3
	v_lshl_add_u32 v3, v8, 7, v3
	v_and_b32_e32 v4, 1, v7
	v_bitop3_b32 v2, v6, s40, v2 bitop3:0xde
	s_mov_b64 s[36:37], 0x220000
	s_waitcnt vmcnt(6)
	v_lshl_or_b32 v3, v4, 6, v3
	s_cmpk_lt_u32 s34, 0x100
	v_lshl_add_u64 v[200:201], v[198:199], 0, s[36:37]
	v_lshl_add_u32 v198, v9, 1, v3
	v_add_u32_e32 v224, 0, v2
	v_mbcnt_lo_u32_b32 v2, -1, 0
	v_cndmask_b32_e64 v6, 0, 1, s[28:29]
	s_cselect_b64 s[28:29], -1, 0
	v_or_b32_e32 v216, 16, v214
	v_or_b32_e32 v217, 32, v214
	v_or_b32_e32 v218, 48, v214
	v_add_u32_e32 v219, 0x80, v214
	v_add_u32_e32 v220, 0x90, v214
	v_add_u32_e32 v221, 0xa0, v214
	v_add_u32_e32 v222, 0xb0, v214
	v_lshl_add_u64 v[202:203], v[198:199], 0, s[36:37]
	v_mov_b64_e32 v[208:209], s[24:25]
	v_mov_b64_e32 v[204:205], 0xe0
	v_mov_b64_e32 v[206:207], 0xdf
	v_mov_b32_e32 v223, 0x4000
	v_add_u32_e32 v225, 0x10000, v224
	v_add_u32_e32 v227, 0x14000, v224
	v_add_u32_e32 v228, 0, v11
	v_mov_b32_e32 v229, 0x358637bd
	s_mov_b32 s24, 0xf800000
	v_mov_b32_e32 v230, 0x260
	s_movk_i32 s67, 0x600
	v_mbcnt_hi_u32_b32 v231, -1, v2
	s_barrier
	s_branch .LBB0_899

.LBB0_903:
	s_mov_b32 m0, s23
	v_lshl_add_u64 v[252:253], s[100:101], 0, v[194:195]
	global_load_lds_dwordx4 v[252:253], off
	s_mov_b32 m0, s31
	v_lshl_add_u64 v[252:253], s[100:101], 0, v[196:197]
	global_load_lds_dwordx4 v[252:253], off
	ds_read_b128 v[146:149], v225
	ds_read_b128 v[150:153], v225 offset:1024
	ds_read_b128 v[154:157], v225 offset:2048
	ds_read_b128 v[158:161], v225 offset:3072
	ds_read_b128 v[130:133], v227
	ds_read_b128 v[134:137], v227 offset:1024
	ds_read_b128 v[138:141], v227 offset:2048
	ds_read_b128 v[142:145], v227 offset:3072
	v_lshl_add_u64 v[234:235], v[210:211], 0, s[62:63]
	s_add_i32 m0, s8, 0xc000
	s_waitcnt lgkmcnt(0)
	ds_read_b128 v[174:177], v228
	ds_read_b128 v[190:193], v228 offset:1024
	ds_read_b128 v[170:173], v228 offset:2048
	ds_read_b128 v[186:189], v228 offset:3072
	ds_read_b128 v[166:169], v228 offset:4096
	ds_read_b128 v[182:185], v228 offset:5120
	ds_read_b128 v[162:165], v228 offset:6144
	ds_read_b128 v[178:181], v228 offset:7168
	global_load_lds_dwordx4 v[234:235], off
	v_lshl_add_u64 v[234:235], v[212:213], 0, s[62:63]
	s_add_i32 m0, s8, 0xe000
	s_nop 0
	global_load_lds_dwordx4 v[234:235], off
	s_waitcnt vmcnt(8)
	s_waitcnt lgkmcnt(0)
	s_barrier
	s_setprio 1
	s_waitcnt lgkmcnt(0)
	v_mfma_f32_16x16x32_bf16 v[126:129], v[146:149], v[174:177], v[126:129]
	v_mfma_f32_16x16x32_bf16 v[122:125], v[154:157], v[174:177], v[122:125]
	v_mfma_f32_16x16x32_bf16 v[118:121], v[146:149], v[170:173], v[118:121]
	v_mfma_f32_16x16x32_bf16 v[114:117], v[154:157], v[170:173], v[114:117]
	v_mfma_f32_16x16x32_bf16 v[110:113], v[146:149], v[166:169], v[110:113]
	v_mfma_f32_16x16x32_bf16 v[106:109], v[154:157], v[166:169], v[106:109]
	v_mfma_f32_16x16x32_bf16 v[102:105], v[146:149], v[162:165], v[102:105]
	v_mfma_f32_16x16x32_bf16 v[98:101], v[154:157], v[162:165], v[98:101]
	v_mfma_f32_16x16x32_bf16 v[126:129], v[150:153], v[190:193], v[126:129]
	v_mfma_f32_16x16x32_bf16 v[122:125], v[158:161], v[190:193], v[122:125]
	v_mfma_f32_16x16x32_bf16 v[118:121], v[150:153], v[186:189], v[118:121]
	v_mfma_f32_16x16x32_bf16 v[114:117], v[158:161], v[186:189], v[114:117]
	v_mfma_f32_16x16x32_bf16 v[110:113], v[150:153], v[182:185], v[110:113]
	v_mfma_f32_16x16x32_bf16 v[106:109], v[158:161], v[182:185], v[106:109]
	v_mfma_f32_16x16x32_bf16 v[102:105], v[150:153], v[178:181], v[102:105]
	v_mfma_f32_16x16x32_bf16 v[98:101], v[158:161], v[178:181], v[98:101]
	s_setprio 0
	s_setprio 1
	v_mfma_f32_16x16x32_bf16 v[94:97], v[130:133], v[174:177], v[94:97]
	v_mfma_f32_16x16x32_bf16 v[90:93], v[138:141], v[174:177], v[90:93]
	v_mfma_f32_16x16x32_bf16 v[86:89], v[130:133], v[170:173], v[86:89]
	v_mfma_f32_16x16x32_bf16 v[82:85], v[138:141], v[170:173], v[82:85]
	v_mfma_f32_16x16x32_bf16 v[78:81], v[130:133], v[166:169], v[78:81]
	v_mfma_f32_16x16x32_bf16 v[74:77], v[138:141], v[166:169], v[74:77]
	v_mfma_f32_16x16x32_bf16 v[70:73], v[130:133], v[162:165], v[70:73]
	v_mfma_f32_16x16x32_bf16 v[66:69], v[138:141], v[162:165], v[66:69]
	v_mfma_f32_16x16x32_bf16 v[94:97], v[134:137], v[190:193], v[94:97]
	v_mfma_f32_16x16x32_bf16 v[90:93], v[142:145], v[190:193], v[90:93]
	v_mfma_f32_16x16x32_bf16 v[86:89], v[134:137], v[186:189], v[86:89]
	v_mfma_f32_16x16x32_bf16 v[82:85], v[142:145], v[186:189], v[82:85]
	v_mfma_f32_16x16x32_bf16 v[78:81], v[134:137], v[182:185], v[78:81]
	v_mfma_f32_16x16x32_bf16 v[74:77], v[142:145], v[182:185], v[74:77]
	v_mfma_f32_16x16x32_bf16 v[70:73], v[134:137], v[178:181], v[70:73]
	v_mfma_f32_16x16x32_bf16 v[66:69], v[142:145], v[178:181], v[66:69]
	s_setprio 0
	s_barrier
	v_cmp_ne_u32_e64 s[42:43], 1, v233
	s_andn2_b64 vcc, exec, s[44:45]
	s_cbranch_vccnz .LBB0_905
	ds_read_b128 v[174:177], v228 offset:16384
	ds_read_b128 v[190:193], v228 offset:17408
	ds_read_b128 v[170:173], v228 offset:18432
	ds_read_b128 v[186:189], v228 offset:19456
	ds_read_b128 v[166:169], v228 offset:20480
	ds_read_b128 v[182:185], v228 offset:21504
	ds_read_b128 v[162:165], v228 offset:22528
	ds_read_b128 v[178:181], v228 offset:23552

.LBB0_909:
	s_add_u32 s72, s68, 0xe0000
	s_addc_u32 s73, s69, 0
	s_add_u32 s70, s70, 0x220000
	s_addc_u32 s71, s71, 0
	s_mov_b32 m0, s16
	v_lshl_add_u64 v[234:235], s[72:73], 0, v[194:195]
	s_add_u32 s68, s68, 0xe4000
	global_load_lds_dwordx4 v[234:235], off
	v_lshl_add_u64 v[234:235], s[72:73], 0, v[196:197]
	s_mov_b32 m0, s17
	s_addc_u32 s69, s69, 0
	global_load_lds_dwordx4 v[234:235], off
	v_lshl_add_u64 v[234:235], s[68:69], 0, v[194:195]
	s_mov_b32 m0, s54
	s_and_b64 vcc, exec, s[42:43]
	global_load_lds_dwordx4 v[234:235], off
	v_lshl_add_u64 v[234:235], s[68:69], 0, v[196:197]
	s_mov_b32 m0, s55
	s_nop 0
	global_load_lds_dwordx4 v[234:235], off
	s_mov_b64 s[100:101], s[70:71]
	s_waitcnt vmcnt(6)
	s_waitcnt lgkmcnt(0)
	s_barrier
	s_cbranch_vccnz .LBB0_902
	s_setprio 1
	s_waitcnt lgkmcnt(0)
	v_mfma_f32_16x16x32_bf16 v[62:65], v[146:149], v[174:177], v[62:65]
	v_mfma_f32_16x16x32_bf16 v[58:61], v[154:157], v[174:177], v[58:61]
	v_mfma_f32_16x16x32_bf16 v[54:57], v[146:149], v[170:173], v[54:57]
	v_mfma_f32_16x16x32_bf16 v[50:53], v[154:157], v[170:173], v[50:53]
	v_mfma_f32_16x16x32_bf16 v[46:49], v[146:149], v[166:169], v[46:49]
	v_mfma_f32_16x16x32_bf16 v[42:45], v[154:157], v[166:169], v[42:45]
	v_mfma_f32_16x16x32_bf16 v[38:41], v[146:149], v[162:165], v[38:41]
	v_mfma_f32_16x16x32_bf16 v[34:37], v[154:157], v[162:165], v[34:37]
	v_mfma_f32_16x16x32_bf16 v[62:65], v[150:153], v[190:193], v[62:65]
	v_mfma_f32_16x16x32_bf16 v[58:61], v[158:161], v[190:193], v[58:61]
	v_mfma_f32_16x16x32_bf16 v[54:57], v[150:153], v[186:189], v[54:57]
	v_mfma_f32_16x16x32_bf16 v[50:53], v[158:161], v[186:189], v[50:53]
	v_mfma_f32_16x16x32_bf16 v[46:49], v[150:153], v[182:185], v[46:49]
	v_mfma_f32_16x16x32_bf16 v[42:45], v[158:161], v[182:185], v[42:45]
	v_mfma_f32_16x16x32_bf16 v[38:41], v[150:153], v[178:181], v[38:41]
	v_mfma_f32_16x16x32_bf16 v[34:37], v[158:161], v[178:181], v[34:37]
	s_setprio 0
	s_setprio 1
	v_mfma_f32_16x16x32_bf16 v[30:33], v[130:133], v[174:177], v[30:33]
	v_mfma_f32_16x16x32_bf16 v[26:29], v[138:141], v[174:177], v[26:29]
	v_mfma_f32_16x16x32_bf16 v[22:25], v[130:133], v[170:173], v[22:25]
	v_mfma_f32_16x16x32_bf16 v[18:21], v[138:141], v[170:173], v[18:21]
	v_mfma_f32_16x16x32_bf16 v[14:17], v[130:133], v[166:169], v[14:17]
	v_mfma_f32_16x16x32_bf16 v[10:13], v[138:141], v[166:169], v[10:13]
	v_mfma_f32_16x16x32_bf16 v[6:9], v[130:133], v[162:165], v[6:9]
	v_mfma_f32_16x16x32_bf16 v[2:5], v[138:141], v[162:165], v[2:5]
	v_mfma_f32_16x16x32_bf16 v[30:33], v[134:137], v[190:193], v[30:33]
	v_mfma_f32_16x16x32_bf16 v[26:29], v[142:145], v[190:193], v[26:29]
	v_mfma_f32_16x16x32_bf16 v[22:25], v[134:137], v[186:189], v[22:25]
	v_mfma_f32_16x16x32_bf16 v[18:21], v[142:145], v[186:189], v[18:21]
	v_mfma_f32_16x16x32_bf16 v[14:17], v[134:137], v[182:185], v[14:17]
	v_mfma_f32_16x16x32_bf16 v[10:13], v[142:145], v[182:185], v[10:13]
	v_mfma_f32_16x16x32_bf16 v[6:9], v[134:137], v[178:181], v[6:9]
	v_mfma_f32_16x16x32_bf16 v[2:5], v[142:145], v[178:181], v[2:5]
	s_setprio 0
	s_branch .LBB0_902

.LBB0_1282:
	v_lshrrev_b32_e32 v10, 1, v2
	v_and_b32_e32 v12, 24, v10
	s_add_u32 s22, s50, 0xea00000
	v_and_b32_e32 v9, 15, v2
	v_lshlrev_b32_e32 v10, 1, v12
	v_lshlrev_b32_e32 v2, 2, v2
	s_addc_u32 s23, s51, 0
	s_lshl_b32 s19, s16, 6
	v_lshl_or_b32 v10, v9, 6, v10
	s_lshl_b32 s16, s16, 13
	v_and_b32_e32 v2, 32, v2
	v_bitop3_b32 v13, v10, s16, v2 bitop3:0xde
	s_lshl_b32 s16, s17, 5
	s_and_b32 s34, s16, 0x60
	s_lshl_b32 s16, s34, 7
	v_bitop3_b32 v14, v10, s16, v2 bitop3:0xde
	v_cndmask_b32_e64 v2, 0, 1, s[24:25]
	s_add_u32 s24, s42, 0x40000
	s_addc_u32 s25, s43, 0
	s_add_i32 s16, s8, 0x18000
	v_lshl_add_u64 v[10:11], s[24:25], 0, v[194:195]
	s_mov_b32 m0, s16
	s_add_i32 s17, s8, 0x1a000
	s_waitcnt vmcnt(2)
	s_barrier
	global_load_lds_dwordx4 v[10:11], off
	v_lshl_add_u64 v[10:11], s[24:25], 0, v[196:197]
	s_add_u32 s24, s36, 0x220000
	s_mov_b32 m0, s17
	s_addc_u32 s25, s37, 0
	s_add_i32 s27, s8, 0x8000
	global_load_lds_dwordx4 v[10:11], off
	v_lshl_add_u64 v[10:11], s[24:25], 0, v[194:195]
	s_mov_b64 s[100:101], s[24:25]
	s_mov_b32 m0, s27
	s_add_i32 s54, s8, 0xa000
	global_load_lds_dwordx4 v[10:11], off
	v_lshl_add_u64 v[10:11], s[24:25], 0, v[196:197]
	s_add_u32 s24, s42, 0x44000
	s_mov_b32 m0, s54
	s_addc_u32 s25, s43, 0
	s_add_i32 s55, s8, 0x1c000
	global_load_lds_dwordx4 v[10:11], off
	v_lshl_add_u64 v[10:11], s[24:25], 0, v[194:195]
	s_mov_b32 m0, s55
	s_add_i32 s60, s8, 0x1e000
	global_load_lds_dwordx4 v[10:11], off
	v_lshl_add_u64 v[10:11], s[24:25], 0, v[196:197]
	s_mov_b32 m0, s60
	v_or_b32_e32 v200, s19, v9
	global_load_lds_dwordx4 v[10:11], off
	v_lshlrev_b32_e32 v9, 10, v3
	v_and_b32_e32 v9, 0xfffff800, v9
	v_lshl_add_u32 v4, v4, 7, v9
	v_and_b32_e32 v3, 1, v3
	s_cmpk_lt_u32 s30, 0x100
	v_lshl_or_b32 v3, v3, 6, v4
	s_cselect_b64 s[24:25], -1, 0
	s_ashr_i32 s30, s19, 31
	v_lshl_add_u32 v198, v5, 1, v3
	v_lshlrev_b32_e32 v3, 10, v6
	v_mov_b32_e32 v201, s30
	v_mov_b32_e32 v203, s30
	v_mov_b32_e32 v205, s30
	v_mov_b32_e32 v207, s30
	s_mov_b64 s[30:31], 0x80
	v_and_b32_e32 v3, 0xfffff800, v3
	v_lshl_add_u64 v[208:209], v[200:201], 0, s[30:31]
	s_mov_b64 s[30:31], 0x90
	v_lshl_add_u32 v3, v7, 7, v3
	v_and_b32_e32 v4, 1, v6
	s_mov_b64 s[28:29], 0x220000
	s_waitcnt vmcnt(6)
	v_lshl_add_u64 v[210:211], v[200:201], 0, s[30:31]
	s_mov_b64 s[30:31], 0xa0
	v_lshl_or_b32 v3, v4, 6, v3
	v_lshl_add_u64 v[212:213], v[200:201], 0, s[30:31]
	s_mov_b64 s[30:31], 0xb0
	v_lshl_add_u64 v[216:217], v[198:199], 0, s[28:29]
	v_lshl_add_u32 v198, v8, 1, v3
	v_add_u32_e32 v229, 0, v14
	v_or_b32_e32 v202, 16, v200
	v_or_b32_e32 v204, 32, v200
	v_or_b32_e32 v206, 48, v200
	v_lshl_add_u64 v[214:215], v[200:201], 0, s[30:31]
	v_or_b32_e32 v227, s34, v12
	v_lshl_add_u64 v[218:219], v[198:199], 0, s[28:29]
	v_mov_b64_e32 v[220:221], s[0:1]
	v_mov_b32_e32 v228, 0x4000
	v_add_u32_e32 v230, 0x10000, v229
	v_add_u32_e32 v231, 0, v13
	s_mov_b32 s0, s1
	s_barrier
	s_branch .LBB0_1285

.LBB0_1289:
	s_mov_b32 m0, s27
	v_lshl_add_u64 v[252:253], s[100:101], 0, v[194:195]
	global_load_lds_dwordx4 v[252:253], off
	s_mov_b32 m0, s54
	v_lshl_add_u64 v[252:253], s[100:101], 0, v[196:197]
	global_load_lds_dwordx4 v[252:253], off
	v_add_u32_e32 v142, 0x14000, v229
	ds_read_b128 v[146:149], v230
	ds_read_b128 v[150:153], v230 offset:1024
	ds_read_b128 v[154:157], v230 offset:2048
	ds_read_b128 v[158:161], v230 offset:3072
	ds_read_b128 v[130:133], v142
	ds_read_b128 v[134:137], v142 offset:1024
	ds_read_b128 v[138:141], v142 offset:2048
	ds_read_b128 v[142:145], v142 offset:3072
	v_lshl_add_u64 v[234:235], v[222:223], 0, s[48:49]
	s_add_i32 m0, s8, 0xc000
	s_waitcnt lgkmcnt(0)
	ds_read_b128 v[174:177], v231
	ds_read_b128 v[190:193], v231 offset:1024
	ds_read_b128 v[170:173], v231 offset:2048
	ds_read_b128 v[186:189], v231 offset:3072
	ds_read_b128 v[166:169], v231 offset:4096
	ds_read_b128 v[182:185], v231 offset:5120
	ds_read_b128 v[162:165], v231 offset:6144
	ds_read_b128 v[178:181], v231 offset:7168
	global_load_lds_dwordx4 v[234:235], off
	v_lshl_add_u64 v[234:235], v[224:225], 0, s[48:49]
	s_add_i32 m0, s8, 0xe000
	s_nop 0
	global_load_lds_dwordx4 v[234:235], off
	s_waitcnt vmcnt(8)
	s_waitcnt lgkmcnt(0)
	s_barrier
	s_setprio 1
	s_waitcnt lgkmcnt(0)
	v_mfma_f32_16x16x32_bf16 v[126:129], v[146:149], v[174:177], v[126:129]
	v_mfma_f32_16x16x32_bf16 v[122:125], v[154:157], v[174:177], v[122:125]
	v_mfma_f32_16x16x32_bf16 v[118:121], v[146:149], v[170:173], v[118:121]
	v_mfma_f32_16x16x32_bf16 v[110:113], v[154:157], v[170:173], v[110:113]
	v_mfma_f32_16x16x32_bf16 v[102:105], v[146:149], v[166:169], v[102:105]
	v_mfma_f32_16x16x32_bf16 v[94:97], v[154:157], v[166:169], v[94:97]
	v_mfma_f32_16x16x32_bf16 v[86:89], v[146:149], v[162:165], v[86:89]
	v_mfma_f32_16x16x32_bf16 v[78:81], v[154:157], v[162:165], v[78:81]
	v_mfma_f32_16x16x32_bf16 v[126:129], v[150:153], v[190:193], v[126:129]
	v_mfma_f32_16x16x32_bf16 v[122:125], v[158:161], v[190:193], v[122:125]
	v_mfma_f32_16x16x32_bf16 v[118:121], v[150:153], v[186:189], v[118:121]
	v_mfma_f32_16x16x32_bf16 v[110:113], v[158:161], v[186:189], v[110:113]
	v_mfma_f32_16x16x32_bf16 v[102:105], v[150:153], v[182:185], v[102:105]
	v_mfma_f32_16x16x32_bf16 v[94:97], v[158:161], v[182:185], v[94:97]
	v_mfma_f32_16x16x32_bf16 v[86:89], v[150:153], v[178:181], v[86:89]
	v_mfma_f32_16x16x32_bf16 v[78:81], v[158:161], v[178:181], v[78:81]
	s_setprio 0
	s_setprio 1
	v_mfma_f32_16x16x32_bf16 v[114:117], v[130:133], v[174:177], v[114:117]
	v_mfma_f32_16x16x32_bf16 v[106:109], v[138:141], v[174:177], v[106:109]
	v_mfma_f32_16x16x32_bf16 v[98:101], v[130:133], v[170:173], v[98:101]
	v_mfma_f32_16x16x32_bf16 v[90:93], v[138:141], v[170:173], v[90:93]
	v_mfma_f32_16x16x32_bf16 v[82:85], v[130:133], v[166:169], v[82:85]
	v_mfma_f32_16x16x32_bf16 v[74:77], v[138:141], v[166:169], v[74:77]
	v_mfma_f32_16x16x32_bf16 v[70:73], v[130:133], v[162:165], v[70:73]
	v_mfma_f32_16x16x32_bf16 v[66:69], v[138:141], v[162:165], v[66:69]
	v_mfma_f32_16x16x32_bf16 v[114:117], v[134:137], v[190:193], v[114:117]
	v_mfma_f32_16x16x32_bf16 v[106:109], v[142:145], v[190:193], v[106:109]
	v_mfma_f32_16x16x32_bf16 v[98:101], v[134:137], v[186:189], v[98:101]
	v_mfma_f32_16x16x32_bf16 v[90:93], v[142:145], v[186:189], v[90:93]
	v_mfma_f32_16x16x32_bf16 v[82:85], v[134:137], v[182:185], v[82:85]
	v_mfma_f32_16x16x32_bf16 v[74:77], v[142:145], v[182:185], v[74:77]
	v_mfma_f32_16x16x32_bf16 v[70:73], v[134:137], v[178:181], v[70:73]
	v_mfma_f32_16x16x32_bf16 v[66:69], v[142:145], v[178:181], v[66:69]
	s_setprio 0
	s_barrier
	v_cndmask_b32_e64 v233, 0, 1, s[40:41]
	v_cmp_ne_u32_e64 s[42:43], 1, v233
	s_andn2_b64 vcc, exec, s[40:41]
	s_cbranch_vccnz .LBB0_1291
	ds_read_b128 v[174:177], v231 offset:16384
	ds_read_b128 v[190:193], v231 offset:17408
	ds_read_b128 v[170:173], v231 offset:18432
	ds_read_b128 v[186:189], v231 offset:19456
	ds_read_b128 v[166:169], v231 offset:20480
	ds_read_b128 v[182:185], v231 offset:21504
	ds_read_b128 v[162:165], v231 offset:22528
	ds_read_b128 v[178:181], v231 offset:23552

.LBB0_1295:
	s_add_u32 s58, s52, 0x40000
	s_addc_u32 s59, s53, 0
	s_add_u32 s56, s56, 0x220000
	s_addc_u32 s57, s57, 0
	s_mov_b32 m0, s16
	v_lshl_add_u64 v[234:235], s[58:59], 0, v[194:195]
	s_add_u32 s52, s52, 0x44000
	global_load_lds_dwordx4 v[234:235], off
	v_lshl_add_u64 v[234:235], s[58:59], 0, v[196:197]
	s_mov_b32 m0, s17
	s_addc_u32 s53, s53, 0
	global_load_lds_dwordx4 v[234:235], off
	v_lshl_add_u64 v[234:235], s[52:53], 0, v[194:195]
	s_mov_b32 m0, s55
	s_and_b64 vcc, exec, s[42:43]
	global_load_lds_dwordx4 v[234:235], off
	v_lshl_add_u64 v[234:235], s[52:53], 0, v[196:197]
	s_mov_b32 m0, s60
	s_nop 0
	global_load_lds_dwordx4 v[234:235], off
	s_mov_b64 s[100:101], s[56:57]
	s_waitcnt vmcnt(6)
	s_waitcnt lgkmcnt(0)
	s_barrier
	s_cbranch_vccnz .LBB0_1288
	s_setprio 1
	s_waitcnt lgkmcnt(0)
	v_mfma_f32_16x16x32_bf16 v[62:65], v[146:149], v[174:177], v[62:65]
	v_mfma_f32_16x16x32_bf16 v[58:61], v[154:157], v[174:177], v[58:61]
	v_mfma_f32_16x16x32_bf16 v[46:49], v[146:149], v[170:173], v[46:49]
	v_mfma_f32_16x16x32_bf16 v[42:45], v[154:157], v[170:173], v[42:45]
	v_mfma_f32_16x16x32_bf16 v[30:33], v[146:149], v[166:169], v[30:33]
	v_mfma_f32_16x16x32_bf16 v[26:29], v[154:157], v[166:169], v[26:29]
	v_mfma_f32_16x16x32_bf16 v[14:17], v[146:149], v[162:165], v[14:17]
	v_mfma_f32_16x16x32_bf16 v[10:13], v[154:157], v[162:165], v[10:13]
	v_mfma_f32_16x16x32_bf16 v[62:65], v[150:153], v[190:193], v[62:65]
	v_mfma_f32_16x16x32_bf16 v[58:61], v[158:161], v[190:193], v[58:61]
	v_mfma_f32_16x16x32_bf16 v[46:49], v[150:153], v[186:189], v[46:49]
	v_mfma_f32_16x16x32_bf16 v[42:45], v[158:161], v[186:189], v[42:45]
	v_mfma_f32_16x16x32_bf16 v[30:33], v[150:153], v[182:185], v[30:33]
	v_mfma_f32_16x16x32_bf16 v[26:29], v[158:161], v[182:185], v[26:29]
	v_mfma_f32_16x16x32_bf16 v[14:17], v[150:153], v[178:181], v[14:17]
	v_mfma_f32_16x16x32_bf16 v[10:13], v[158:161], v[178:181], v[10:13]
	s_setprio 0
	s_setprio 1
	v_mfma_f32_16x16x32_bf16 v[54:57], v[130:133], v[174:177], v[54:57]
	v_mfma_f32_16x16x32_bf16 v[50:53], v[138:141], v[174:177], v[50:53]
	v_mfma_f32_16x16x32_bf16 v[38:41], v[130:133], v[170:173], v[38:41]
	v_mfma_f32_16x16x32_bf16 v[34:37], v[138:141], v[170:173], v[34:37]
	v_mfma_f32_16x16x32_bf16 v[22:25], v[130:133], v[166:169], v[22:25]
	v_mfma_f32_16x16x32_bf16 v[18:21], v[138:141], v[166:169], v[18:21]
	v_mfma_f32_16x16x32_bf16 v[6:9], v[130:133], v[162:165], v[6:9]
	v_mfma_f32_16x16x32_bf16 v[2:5], v[138:141], v[162:165], v[2:5]
	v_mfma_f32_16x16x32_bf16 v[54:57], v[134:137], v[190:193], v[54:57]
	v_mfma_f32_16x16x32_bf16 v[50:53], v[142:145], v[190:193], v[50:53]
	v_mfma_f32_16x16x32_bf16 v[38:41], v[134:137], v[186:189], v[38:41]
	v_mfma_f32_16x16x32_bf16 v[34:37], v[142:145], v[186:189], v[34:37]
	v_mfma_f32_16x16x32_bf16 v[22:25], v[134:137], v[182:185], v[22:25]
	v_mfma_f32_16x16x32_bf16 v[18:21], v[142:145], v[182:185], v[18:21]
	v_mfma_f32_16x16x32_bf16 v[6:9], v[134:137], v[178:181], v[6:9]
	v_mfma_f32_16x16x32_bf16 v[2:5], v[142:145], v[178:181], v[2:5]
	s_setprio 0
	s_branch .LBB0_1288

.LBB0_1601:
	s_add_u32 s24, s24, 0xea00000
	s_addc_u32 s25, s25, 0
	s_lshl_b32 s19, s17, 6
	s_lshl_b32 s31, s17, 13
	s_lshl_b32 s17, s27, 5
	s_and_b32 s38, s17, 0x60
	s_lshl_b32 s27, s38, 7
	s_add_u32 s34, s42, 0x40000
	s_addc_u32 s35, s43, 0
	s_add_i32 s17, s9, 0x18000
	v_lshl_add_u64 v[10:11], s[34:35], 0, v[194:195]
	s_mov_b32 m0, s17
	s_add_i32 s29, s9, 0x1a000
	s_waitcnt vmcnt(2)
	s_barrier
	global_load_lds_dwordx4 v[10:11], off
	v_lshl_add_u64 v[10:11], s[34:35], 0, v[196:197]
	s_add_u32 s34, s46, 0x220000
	s_mov_b32 m0, s29
	s_addc_u32 s35, s47, 0
	s_add_i32 s54, s9, 0x8000
	global_load_lds_dwordx4 v[10:11], off
	v_lshl_add_u64 v[10:11], s[34:35], 0, v[194:195]
	s_mov_b64 s[100:101], s[34:35]
	s_mov_b32 m0, s54
	s_add_i32 s55, s9, 0xa000
	global_load_lds_dwordx4 v[10:11], off
	v_lshl_add_u64 v[10:11], s[34:35], 0, v[196:197]
	s_add_u32 s34, s42, 0x44000
	s_mov_b32 m0, s55
	s_addc_u32 s35, s43, 0
	s_add_i32 s58, s9, 0x1c000
	global_load_lds_dwordx4 v[10:11], off
	v_lshl_add_u64 v[10:11], s[34:35], 0, v[194:195]
	s_mov_b32 m0, s58
	s_add_i32 s59, s9, 0x1e000
	global_load_lds_dwordx4 v[10:11], off
	v_lshl_add_u64 v[10:11], s[34:35], 0, v[196:197]
	s_mov_b32 m0, s59
	v_and_b32_e32 v9, 15, v2
	global_load_lds_dwordx4 v[10:11], off
	v_lshrrev_b32_e32 v10, 1, v2
	v_and_b32_e32 v10, 24, v10
	v_lshlrev_b32_e32 v11, 1, v10
	v_lshl_or_b32 v11, v9, 6, v11
	v_or_b32_e32 v200, s19, v9
	v_lshlrev_b32_e32 v9, 10, v3
	v_and_b32_e32 v9, 0xfffff800, v9
	v_lshlrev_b32_e32 v2, 2, v2
	v_lshl_add_u32 v4, v4, 7, v9
	v_and_b32_e32 v3, 1, v3
	v_and_b32_e32 v2, 32, v2
	s_cmpk_lt_u32 s26, 0x100
	v_lshl_or_b32 v3, v3, 6, v4
	v_bitop3_b32 v12, v11, s31, v2 bitop3:0xde
	v_bitop3_b32 v2, v11, s27, v2 bitop3:0xde
	s_cselect_b64 s[26:27], -1, 0
	s_ashr_i32 s36, s19, 31
	v_lshl_add_u32 v198, v5, 1, v3
	v_lshlrev_b32_e32 v3, 10, v6
	v_mov_b32_e32 v201, s36
	v_mov_b32_e32 v203, s36
	v_mov_b32_e32 v205, s36
	v_mov_b32_e32 v207, s36
	s_mov_b64 s[36:37], 0x80
	v_and_b32_e32 v3, 0xfffff800, v3
	v_lshl_add_u64 v[208:209], v[200:201], 0, s[36:37]
	s_mov_b64 s[36:37], 0x90
	v_lshl_add_u32 v3, v7, 7, v3
	v_and_b32_e32 v4, 1, v6
	s_mov_b64 s[34:35], 0x220000
	s_waitcnt vmcnt(6)
	v_lshl_add_u64 v[210:211], v[200:201], 0, s[36:37]
	s_mov_b64 s[36:37], 0xa0
	v_lshl_or_b32 v3, v4, 6, v3
	s_mov_b32 s31, s21
	v_lshl_add_u64 v[212:213], v[200:201], 0, s[36:37]
	s_mov_b64 s[36:37], 0xb0
	v_lshl_add_u64 v[216:217], v[198:199], 0, s[34:35]
	v_lshl_add_u32 v198, v8, 1, v3
	v_or_b32_e32 v202, 16, v200
	v_or_b32_e32 v204, 32, v200
	v_or_b32_e32 v206, 48, v200
	v_lshl_add_u64 v[214:215], v[200:201], 0, s[36:37]
	v_or_b32_e32 v230, s38, v10
	v_lshl_add_u64 v[218:219], v[198:199], 0, s[34:35]
	v_mov_b64_e32 v[224:225], s[20:21]
	v_mov_b64_e32 v[220:221], s[30:31]
	v_mov_b32_e32 v231, 0x4000
	v_mov_b64_e32 v[222:223], 0x1ff
	v_add_u32_e32 v232, 0, v2
	v_add_u32_e32 v233, 0, v12
	s_barrier
	s_waitcnt vmcnt(0)
	s_branch .LBB0_1604

.LBB0_1612:
	s_mov_b32 m0, s54
	v_lshl_add_u64 v[252:253], s[100:101], 0, v[194:195]
	global_load_lds_dwordx4 v[252:253], off
	s_mov_b32 m0, s55
	v_lshl_add_u64 v[252:253], s[100:101], 0, v[196:197]
	global_load_lds_dwordx4 v[252:253], off
	v_add_u32_e32 v1, 0x10000, v232
	ds_read_b128 v[146:149], v1
	ds_read_b128 v[150:153], v1 offset:1024
	ds_read_b128 v[154:157], v1 offset:2048
	ds_read_b128 v[158:161], v1 offset:3072
	v_add_u32_e32 v1, 0x14000, v232
	ds_read_b128 v[130:133], v1
	ds_read_b128 v[134:137], v1 offset:1024
	ds_read_b128 v[138:141], v1 offset:2048
	ds_read_b128 v[142:145], v1 offset:3072
	v_lshl_add_u64 v[236:237], v[226:227], 0, s[48:49]
	s_add_i32 m0, s9, 0xc000
	s_waitcnt lgkmcnt(0)
	ds_read_b128 v[174:177], v233
	ds_read_b128 v[190:193], v233 offset:1024
	ds_read_b128 v[170:173], v233 offset:2048
	ds_read_b128 v[186:189], v233 offset:3072
	ds_read_b128 v[166:169], v233 offset:4096
	ds_read_b128 v[182:185], v233 offset:5120
	ds_read_b128 v[162:165], v233 offset:6144
	ds_read_b128 v[178:181], v233 offset:7168
	global_load_lds_dwordx4 v[236:237], off
	v_lshl_add_u64 v[236:237], v[228:229], 0, s[48:49]
	s_add_i32 m0, s9, 0xe000
	s_nop 0
	global_load_lds_dwordx4 v[236:237], off
	s_waitcnt vmcnt(8)
	s_waitcnt lgkmcnt(0)
	s_barrier
	s_setprio 1
	s_waitcnt lgkmcnt(0)
	v_mfma_f32_16x16x32_bf16 v[126:129], v[146:149], v[174:177], v[126:129]
	v_mfma_f32_16x16x32_bf16 v[122:125], v[154:157], v[174:177], v[122:125]
	v_mfma_f32_16x16x32_bf16 v[118:121], v[146:149], v[170:173], v[118:121]
	v_mfma_f32_16x16x32_bf16 v[110:113], v[154:157], v[170:173], v[110:113]
	v_mfma_f32_16x16x32_bf16 v[102:105], v[146:149], v[166:169], v[102:105]
	v_mfma_f32_16x16x32_bf16 v[94:97], v[154:157], v[166:169], v[94:97]
	v_mfma_f32_16x16x32_bf16 v[86:89], v[146:149], v[162:165], v[86:89]
	v_mfma_f32_16x16x32_bf16 v[78:81], v[154:157], v[162:165], v[78:81]
	v_mfma_f32_16x16x32_bf16 v[126:129], v[150:153], v[190:193], v[126:129]
	v_mfma_f32_16x16x32_bf16 v[122:125], v[158:161], v[190:193], v[122:125]
	v_mfma_f32_16x16x32_bf16 v[118:121], v[150:153], v[186:189], v[118:121]
	v_mfma_f32_16x16x32_bf16 v[110:113], v[158:161], v[186:189], v[110:113]
	v_mfma_f32_16x16x32_bf16 v[102:105], v[150:153], v[182:185], v[102:105]
	v_mfma_f32_16x16x32_bf16 v[94:97], v[158:161], v[182:185], v[94:97]
	v_mfma_f32_16x16x32_bf16 v[86:89], v[150:153], v[178:181], v[86:89]
	v_mfma_f32_16x16x32_bf16 v[78:81], v[158:161], v[178:181], v[78:81]
	s_setprio 0
	s_setprio 1
	v_mfma_f32_16x16x32_bf16 v[114:117], v[130:133], v[174:177], v[114:117]
	v_mfma_f32_16x16x32_bf16 v[106:109], v[138:141], v[174:177], v[106:109]
	v_mfma_f32_16x16x32_bf16 v[98:101], v[130:133], v[170:173], v[98:101]
	v_mfma_f32_16x16x32_bf16 v[90:93], v[138:141], v[170:173], v[90:93]
	v_mfma_f32_16x16x32_bf16 v[82:85], v[130:133], v[166:169], v[82:85]
	v_mfma_f32_16x16x32_bf16 v[74:77], v[138:141], v[166:169], v[74:77]
	v_mfma_f32_16x16x32_bf16 v[70:73], v[130:133], v[162:165], v[70:73]
	v_mfma_f32_16x16x32_bf16 v[66:69], v[138:141], v[162:165], v[66:69]
	v_mfma_f32_16x16x32_bf16 v[114:117], v[134:137], v[190:193], v[114:117]
	v_mfma_f32_16x16x32_bf16 v[106:109], v[142:145], v[190:193], v[106:109]
	v_mfma_f32_16x16x32_bf16 v[98:101], v[134:137], v[186:189], v[98:101]
	v_mfma_f32_16x16x32_bf16 v[90:93], v[142:145], v[186:189], v[90:93]
	v_mfma_f32_16x16x32_bf16 v[82:85], v[134:137], v[182:185], v[82:85]
	v_mfma_f32_16x16x32_bf16 v[74:77], v[142:145], v[182:185], v[74:77]
	v_mfma_f32_16x16x32_bf16 v[70:73], v[134:137], v[178:181], v[70:73]
	v_mfma_f32_16x16x32_bf16 v[66:69], v[142:145], v[178:181], v[66:69]
	s_setprio 0
	s_barrier
	v_cndmask_b32_e64 v1, 0, 1, s[40:41]
	v_cmp_ne_u32_e64 s[42:43], 1, v1
	s_andn2_b64 vcc, exec, s[40:41]
	s_cbranch_vccnz .LBB0_1614
	ds_read_b128 v[174:177], v233 offset:16384
	ds_read_b128 v[190:193], v233 offset:17408
	ds_read_b128 v[170:173], v233 offset:18432
	ds_read_b128 v[186:189], v233 offset:19456
	ds_read_b128 v[166:169], v233 offset:20480
	ds_read_b128 v[182:185], v233 offset:21504
	ds_read_b128 v[162:165], v233 offset:22528
	ds_read_b128 v[178:181], v233 offset:23552

.LBB0_1618:
	s_add_u32 s56, s50, 0x40000
	s_addc_u32 s57, s51, 0
	s_add_u32 s52, s52, 0x220000
	s_addc_u32 s53, s53, 0
	s_mov_b32 m0, s17
	v_lshl_add_u64 v[236:237], s[56:57], 0, v[194:195]
	s_add_u32 s50, s50, 0x44000
	global_load_lds_dwordx4 v[236:237], off
	v_lshl_add_u64 v[236:237], s[56:57], 0, v[196:197]
	s_mov_b32 m0, s29
	s_addc_u32 s51, s51, 0
	global_load_lds_dwordx4 v[236:237], off
	v_lshl_add_u64 v[236:237], s[50:51], 0, v[194:195]
	s_mov_b32 m0, s58
	s_and_b64 vcc, exec, s[42:43]
	global_load_lds_dwordx4 v[236:237], off
	v_lshl_add_u64 v[236:237], s[50:51], 0, v[196:197]
	s_mov_b32 m0, s59
	s_nop 0
	global_load_lds_dwordx4 v[236:237], off
	s_mov_b64 s[100:101], s[52:53]
	s_waitcnt vmcnt(6)
	s_waitcnt lgkmcnt(0)
	s_barrier
	s_cbranch_vccnz .LBB0_1611
	s_setprio 1
	s_waitcnt lgkmcnt(0)
	v_mfma_f32_16x16x32_bf16 v[62:65], v[146:149], v[174:177], v[62:65]
	v_mfma_f32_16x16x32_bf16 v[58:61], v[154:157], v[174:177], v[58:61]
	v_mfma_f32_16x16x32_bf16 v[46:49], v[146:149], v[170:173], v[46:49]
	v_mfma_f32_16x16x32_bf16 v[42:45], v[154:157], v[170:173], v[42:45]
	v_mfma_f32_16x16x32_bf16 v[30:33], v[146:149], v[166:169], v[30:33]
	v_mfma_f32_16x16x32_bf16 v[26:29], v[154:157], v[166:169], v[26:29]
	v_mfma_f32_16x16x32_bf16 v[14:17], v[146:149], v[162:165], v[14:17]
	v_mfma_f32_16x16x32_bf16 v[10:13], v[154:157], v[162:165], v[10:13]
	v_mfma_f32_16x16x32_bf16 v[62:65], v[150:153], v[190:193], v[62:65]
	v_mfma_f32_16x16x32_bf16 v[58:61], v[158:161], v[190:193], v[58:61]
	v_mfma_f32_16x16x32_bf16 v[46:49], v[150:153], v[186:189], v[46:49]
	v_mfma_f32_16x16x32_bf16 v[42:45], v[158:161], v[186:189], v[42:45]
	v_mfma_f32_16x16x32_bf16 v[30:33], v[150:153], v[182:185], v[30:33]
	v_mfma_f32_16x16x32_bf16 v[26:29], v[158:161], v[182:185], v[26:29]
	v_mfma_f32_16x16x32_bf16 v[14:17], v[150:153], v[178:181], v[14:17]
	v_mfma_f32_16x16x32_bf16 v[10:13], v[158:161], v[178:181], v[10:13]
	s_setprio 0
	s_setprio 1
	v_mfma_f32_16x16x32_bf16 v[54:57], v[130:133], v[174:177], v[54:57]
	v_mfma_f32_16x16x32_bf16 v[50:53], v[138:141], v[174:177], v[50:53]
	v_mfma_f32_16x16x32_bf16 v[38:41], v[130:133], v[170:173], v[38:41]
	v_mfma_f32_16x16x32_bf16 v[34:37], v[138:141], v[170:173], v[34:37]
	v_mfma_f32_16x16x32_bf16 v[22:25], v[130:133], v[166:169], v[22:25]
	v_mfma_f32_16x16x32_bf16 v[18:21], v[138:141], v[166:169], v[18:21]
	v_mfma_f32_16x16x32_bf16 v[6:9], v[130:133], v[162:165], v[6:9]
	v_mfma_f32_16x16x32_bf16 v[2:5], v[138:141], v[162:165], v[2:5]
	v_mfma_f32_16x16x32_bf16 v[54:57], v[134:137], v[190:193], v[54:57]
	v_mfma_f32_16x16x32_bf16 v[50:53], v[142:145], v[190:193], v[50:53]
	v_mfma_f32_16x16x32_bf16 v[38:41], v[134:137], v[186:189], v[38:41]
	v_mfma_f32_16x16x32_bf16 v[34:37], v[142:145], v[186:189], v[34:37]
	v_mfma_f32_16x16x32_bf16 v[22:25], v[134:137], v[182:185], v[22:25]
	v_mfma_f32_16x16x32_bf16 v[18:21], v[142:145], v[182:185], v[18:21]
	v_mfma_f32_16x16x32_bf16 v[6:9], v[134:137], v[178:181], v[6:9]
	v_mfma_f32_16x16x32_bf16 v[2:5], v[142:145], v[178:181], v[2:5]
	s_setprio 0
	s_branch .LBB0_1611

	.amdhsa_kernel _Z8yoco_fwd4Args
		.amdhsa_group_segment_fixed_size 0
		.amdhsa_private_segment_fixed_size 0
		.amdhsa_kernarg_size 440
		.amdhsa_user_sgpr_count 2
		.amdhsa_user_sgpr_dispatch_ptr 0
		.amdhsa_user_sgpr_queue_ptr 0
		.amdhsa_user_sgpr_kernarg_segment_ptr 1
		.amdhsa_user_sgpr_dispatch_id 0
		.amdhsa_user_sgpr_kernarg_preload_length 0
		.amdhsa_user_sgpr_kernarg_preload_offset 0
		.amdhsa_user_sgpr_private_segment_size 0
		.amdhsa_uses_dynamic_stack 0
		.amdhsa_enable_private_segment 0
		.amdhsa_system_sgpr_workgroup_id_x 1
		.amdhsa_system_sgpr_workgroup_id_y 0
		.amdhsa_system_sgpr_workgroup_id_z 0
		.amdhsa_system_sgpr_workgroup_info 0
		.amdhsa_system_vgpr_workitem_id 0
		.amdhsa_next_free_vgpr 256
		.amdhsa_next_free_sgpr 102
		.amdhsa_accum_offset 256
		.amdhsa_reserve_vcc 1
		.amdhsa_float_round_mode_32 0
		.amdhsa_float_round_mode_16_64 0
		.amdhsa_float_denorm_mode_32 3
		.amdhsa_float_denorm_mode_16_64 3
		.amdhsa_dx10_clamp 1
		.amdhsa_ieee_mode 1
		.amdhsa_fp16_overflow 0
		.amdhsa_tg_split 0
		.amdhsa_exception_fp_ieee_invalid_op 0
		.amdhsa_exception_fp_denorm_src 0
		.amdhsa_exception_fp_ieee_div_zero 0
		.amdhsa_exception_fp_ieee_overflow 0
		.amdhsa_exception_fp_ieee_underflow 0
		.amdhsa_exception_fp_ieee_inexact 0
		.amdhsa_exception_int_div_zero 0
	.end_amdhsa_kernel

amdhsa.kernels:
  - .agpr_count:     0
    .args:
      - .offset:         0
        .size:           184
        .value_kind:     by_value
      - .offset:         184
        .size:           4
        .value_kind:     hidden_block_count_x
      - .offset:         188
        .size:           4
        .value_kind:     hidden_block_count_y
      - .offset:         192
        .size:           4
        .value_kind:     hidden_block_count_z
      - .offset:         196
        .size:           2
        .value_kind:     hidden_group_size_x
      - .offset:         198
        .size:           2
        .value_kind:     hidden_group_size_y
      - .offset:         200
        .size:           2
        .value_kind:     hidden_group_size_z
      - .offset:         202
        .size:           2
        .value_kind:     hidden_remainder_x
      - .offset:         204
        .size:           2
        .value_kind:     hidden_remainder_y
      - .offset:         206
        .size:           2
        .value_kind:     hidden_remainder_z
      - .offset:         224
        .size:           8
        .value_kind:     hidden_global_offset_x
      - .offset:         232
        .size:           8
        .value_kind:     hidden_global_offset_y
      - .offset:         240
        .size:           8
        .value_kind:     hidden_global_offset_z
      - .offset:         248
        .size:           2
        .value_kind:     hidden_grid_dims
      - .offset:         304
        .size:           4
        .value_kind:     hidden_dynamic_lds_size
    .group_segment_fixed_size: 0
    .kernarg_segment_align: 8
    .kernarg_segment_size: 440
    .language:       OpenCL C
    .language_version:
      - 2
      - 0
    .max_flat_workgroup_size: 512
    .name:           _Z8yoco_fwd4Args
    .private_segment_fixed_size: 0
    .sgpr_count:     108
    .sgpr_spill_count: 153
    .symbol:         _Z8yoco_fwd4Args.kd
    .uniform_work_group_size: 1
    .uses_dynamic_stack: false
    .vgpr_count:     256
    .vgpr_spill_count: 0
    .wavefront_size: 64
